# S5 carry scan (phase 12) hand-written: chunk-final-state loads run two 16-chunk batches ahead of the f32 recurrence with counted vmcnt (was one batch ahead, latency-bound)
# speedup vs baseline: 1.0063x; 1.0063x over previous
.LBB0_893:
	s_waitcnt vmcnt(0)
	v_cndmask_b32_e64 v0, 0, 1, s[0:1]
	v_cmp_ne_u32_e64 s[6:7], 1, v0
	s_andn2_b64 vcc, exec, s[0:1]
	s_waitcnt vmcnt(0) lgkmcnt(0)
	s_barrier
	s_cbranch_vccnz .LBB0_910
	v_mov_b32_e32 v3, 0
	global_load_dwordx2 v[12:13], v3, s[96:97] offset:40 sc0
	global_load_dwordx2 v[14:15], v3, s[96:97] offset:48 sc0
	v_mbcnt_lo_u32_b32 v0, -1, 0
	v_mbcnt_hi_u32_b32 v0, -1, v0
	v_lshlrev_b32_e32 v1, 3, v0
	v_lshlrev_b32_e32 v2, 2, v0
	s_movk_i32 s42, 0x200
	s_mul_i32 s16, s20, 3
	s_sub_i32 s35, s2, s16
	s_and_b32 s25, s94, 1
	s_lshr_b32 s21, s94, 1
	s_lshl_b32 s16, s25, 5
	s_add_i32 s16, s16, s20
	s_mul_i32 s16, s16, 17
	s_add_i32 s16, s16, 16
	s_lshl_b32 s16, s16, 9
	s_add_u32 s74, s54, 0x40000
	s_addc_u32 s75, s55, 0
	s_add_u32 s74, s74, s16
	s_addc_u32 s75, s75, 0
	global_load_dwordx2 v[4:5], v1, s[74:75]
	s_mov_b32 s10, 0xfffffc00
	s_cmp_eq_u32 s25, 0
	s_cselect_b32 s10, 0x400, s10
	s_cselect_b32 s11, 0, -1
	s_waitcnt vmcnt(1)
	v_readfirstlane_b32 s70, v12
	v_readfirstlane_b32 s71, v13
	v_readfirstlane_b32 s72, v14
	v_readfirstlane_b32 s73, v15
	s_cmp_eq_u32 s35, 0
	s_cbranch_scc1 .Lscan_ctx
	s_cmp_gt_u32 s94, 3
	s_cbranch_scc1 .Lscan_end
	s_lshl_b32 s16, s35, 1
	s_add_i32 s16, s16, s21
	s_sub_i32 s16, s16, 2
	s_lshl_b32 s19, s16, 7
	s_add_i32 s19, s19, 0x100
	s_mul_i32 s17, s20, 0x300
	s_add_i32 s17, s17, s19
	s_mul_i32 s18, s25, 127
	s_add_i32 s17, s17, s18
	s_lshl_b32 s17, s17, 10
	s_lshl_b32 s18, s25, 9
	s_add_u32 s0, s54, 0x4200000
	s_addc_u32 s1, s55, 0
	s_add_u32 s0, s0, s17
	s_addc_u32 s1, s1, 0
	s_add_u32 s0, s0, s18
	s_addc_u32 s1, s1, 0
	s_lshl_b32 s18, s25, 8
	s_add_u32 s8, s54, 0xa200000
	s_addc_u32 s9, s55, 0
	s_add_u32 s8, s8, s17
	s_addc_u32 s9, s9, 0
	s_add_u32 s8, s8, s18
	s_addc_u32 s9, s9, 0
	s_add_u32 s8, s8, 0x200
	s_addc_u32 s9, s9, 0
	global_load_dwordx2 v[32:33], v1, s[0:1]
	s_add_u32 s0, s0, s10
	s_addc_u32 s1, s1, s11
	global_load_dwordx2 v[34:35], v1, s[0:1]
	s_add_u32 s0, s0, s10
	s_addc_u32 s1, s1, s11
	global_load_dwordx2 v[36:37], v1, s[0:1]
	s_add_u32 s0, s0, s10
	s_addc_u32 s1, s1, s11
	global_load_dwordx2 v[38:39], v1, s[0:1]
	s_add_u32 s0, s0, s10
	s_addc_u32 s1, s1, s11
	global_load_dwordx2 v[40:41], v1, s[0:1]
	s_add_u32 s0, s0, s10
	s_addc_u32 s1, s1, s11
	global_load_dwordx2 v[42:43], v1, s[0:1]
	s_add_u32 s0, s0, s10
	s_addc_u32 s1, s1, s11
	global_load_dwordx2 v[44:45], v1, s[0:1]
	s_add_u32 s0, s0, s10
	s_addc_u32 s1, s1, s11
	global_load_dwordx2 v[46:47], v1, s[0:1]
	s_add_u32 s0, s0, s10
	s_addc_u32 s1, s1, s11
	global_load_dwordx2 v[48:49], v1, s[0:1]
	s_add_u32 s0, s0, s10
	s_addc_u32 s1, s1, s11
	global_load_dwordx2 v[50:51], v1, s[0:1]
	s_add_u32 s0, s0, s10
	s_addc_u32 s1, s1, s11
	global_load_dwordx2 v[52:53], v1, s[0:1]
	s_add_u32 s0, s0, s10
	s_addc_u32 s1, s1, s11
	global_load_dwordx2 v[54:55], v1, s[0:1]
	s_add_u32 s0, s0, s10
	s_addc_u32 s1, s1, s11
	global_load_dwordx2 v[56:57], v1, s[0:1]
	s_add_u32 s0, s0, s10
	s_addc_u32 s1, s1, s11
	global_load_dwordx2 v[58:59], v1, s[0:1]
	s_add_u32 s0, s0, s10
	s_addc_u32 s1, s1, s11
	global_load_dwordx2 v[60:61], v1, s[0:1]
	s_add_u32 s0, s0, s10
	s_addc_u32 s1, s1, s11
	global_load_dwordx2 v[62:63], v1, s[0:1]
	s_add_u32 s0, s0, s10
	s_addc_u32 s1, s1, s11
	global_load_dwordx2 v[64:65], v1, s[0:1]
	s_add_u32 s0, s0, s10
	s_addc_u32 s1, s1, s11
	global_load_dwordx2 v[66:67], v1, s[0:1]
	s_add_u32 s0, s0, s10
	s_addc_u32 s1, s1, s11
	global_load_dwordx2 v[68:69], v1, s[0:1]
	s_add_u32 s0, s0, s10
	s_addc_u32 s1, s1, s11
	global_load_dwordx2 v[70:71], v1, s[0:1]
	s_add_u32 s0, s0, s10
	s_addc_u32 s1, s1, s11
	global_load_dwordx2 v[72:73], v1, s[0:1]
	s_add_u32 s0, s0, s10
	s_addc_u32 s1, s1, s11
	global_load_dwordx2 v[74:75], v1, s[0:1]
	s_add_u32 s0, s0, s10
	s_addc_u32 s1, s1, s11
	global_load_dwordx2 v[76:77], v1, s[0:1]
	s_add_u32 s0, s0, s10
	s_addc_u32 s1, s1, s11
	global_load_dwordx2 v[78:79], v1, s[0:1]
	s_add_u32 s0, s0, s10
	s_addc_u32 s1, s1, s11
	global_load_dwordx2 v[80:81], v1, s[0:1]
	s_add_u32 s0, s0, s10
	s_addc_u32 s1, s1, s11
	global_load_dwordx2 v[82:83], v1, s[0:1]
	s_add_u32 s0, s0, s10
	s_addc_u32 s1, s1, s11
	global_load_dwordx2 v[84:85], v1, s[0:1]
	s_add_u32 s0, s0, s10
	s_addc_u32 s1, s1, s11
	global_load_dwordx2 v[86:87], v1, s[0:1]
	s_add_u32 s0, s0, s10
	s_addc_u32 s1, s1, s11
	global_load_dwordx2 v[88:89], v1, s[0:1]
	s_add_u32 s0, s0, s10
	s_addc_u32 s1, s1, s11
	global_load_dwordx2 v[90:91], v1, s[0:1]
	s_add_u32 s0, s0, s10
	s_addc_u32 s1, s1, s11
	global_load_dwordx2 v[92:93], v1, s[0:1]
	s_add_u32 s0, s0, s10
	s_addc_u32 s1, s1, s11
	global_load_dwordx2 v[94:95], v1, s[0:1]
	s_add_u32 s0, s0, s10
	s_addc_u32 s1, s1, s11
	s_lshl_b32 s17, s16, 1
	s_add_i32 s17, s17, s25
	s_lshl_b32 s17, s17, 5
	s_add_i32 s17, s17, s20
	s_lshl_b32 s17, s17, 8
	s_add_u32 s70, s70, s17
	s_addc_u32 s71, s71, 0
	s_add_u32 s72, s72, s17
	s_addc_u32 s73, s73, 0
	global_load_dword v6, v2, s[70:71]
	global_load_dword v7, v2, s[72:73]
	s_waitcnt vmcnt(18)
	s_waitcnt vmcnt(0)
	v_cvt_pk_bf16_f32 v8, v6, v7
	global_store_dword v2, v8, s[8:9]
	s_add_u32 s8, s8, s10
	s_addc_u32 s9, s9, s11
	v_mul_f32_e32 v9, v5, v7
	v_mul_f32_e32 v10, v5, v6
	v_fma_f32 v9, v4, v6, -v9
	v_fma_f32 v10, v4, v7, v10
	v_add_f32_e32 v6, v9, v32
	v_add_f32_e32 v7, v10, v33
	v_cvt_pk_bf16_f32 v8, v6, v7
	global_store_dword v2, v8, s[8:9]
	s_add_u32 s8, s8, s10
	s_addc_u32 s9, s9, s11
	v_mul_f32_e32 v9, v5, v7
	v_mul_f32_e32 v10, v5, v6
	v_fma_f32 v9, v4, v6, -v9
	v_fma_f32 v10, v4, v7, v10
	v_add_f32_e32 v6, v9, v34
	v_add_f32_e32 v7, v10, v35
	v_cvt_pk_bf16_f32 v8, v6, v7
	global_store_dword v2, v8, s[8:9]
	s_add_u32 s8, s8, s10
	s_addc_u32 s9, s9, s11
	v_mul_f32_e32 v9, v5, v7
	v_mul_f32_e32 v10, v5, v6
	v_fma_f32 v9, v4, v6, -v9
	v_fma_f32 v10, v4, v7, v10
	v_add_f32_e32 v6, v9, v36
	v_add_f32_e32 v7, v10, v37
	v_cvt_pk_bf16_f32 v8, v6, v7
	global_store_dword v2, v8, s[8:9]
	s_add_u32 s8, s8, s10
	s_addc_u32 s9, s9, s11
	v_mul_f32_e32 v9, v5, v7
	v_mul_f32_e32 v10, v5, v6
	v_fma_f32 v9, v4, v6, -v9
	v_fma_f32 v10, v4, v7, v10
	v_add_f32_e32 v6, v9, v38
	v_add_f32_e32 v7, v10, v39
	v_cvt_pk_bf16_f32 v8, v6, v7
	global_store_dword v2, v8, s[8:9]
	s_add_u32 s8, s8, s10
	s_addc_u32 s9, s9, s11
	v_mul_f32_e32 v9, v5, v7
	v_mul_f32_e32 v10, v5, v6
	v_fma_f32 v9, v4, v6, -v9
	v_fma_f32 v10, v4, v7, v10
	v_add_f32_e32 v6, v9, v40
	v_add_f32_e32 v7, v10, v41
	v_cvt_pk_bf16_f32 v8, v6, v7
	global_store_dword v2, v8, s[8:9]
	s_add_u32 s8, s8, s10
	s_addc_u32 s9, s9, s11
	v_mul_f32_e32 v9, v5, v7
	v_mul_f32_e32 v10, v5, v6
	v_fma_f32 v9, v4, v6, -v9
	v_fma_f32 v10, v4, v7, v10
	v_add_f32_e32 v6, v9, v42
	v_add_f32_e32 v7, v10, v43
	v_cvt_pk_bf16_f32 v8, v6, v7
	global_store_dword v2, v8, s[8:9]
	s_add_u32 s8, s8, s10
	s_addc_u32 s9, s9, s11
	v_mul_f32_e32 v9, v5, v7
	v_mul_f32_e32 v10, v5, v6
	v_fma_f32 v9, v4, v6, -v9
	v_fma_f32 v10, v4, v7, v10
	v_add_f32_e32 v6, v9, v44
	v_add_f32_e32 v7, v10, v45
	v_cvt_pk_bf16_f32 v8, v6, v7
	global_store_dword v2, v8, s[8:9]
	s_add_u32 s8, s8, s10
	s_addc_u32 s9, s9, s11
	v_mul_f32_e32 v9, v5, v7
	v_mul_f32_e32 v10, v5, v6
	v_fma_f32 v9, v4, v6, -v9
	v_fma_f32 v10, v4, v7, v10
	v_add_f32_e32 v6, v9, v46
	v_add_f32_e32 v7, v10, v47
	v_cvt_pk_bf16_f32 v8, v6, v7
	global_store_dword v2, v8, s[8:9]
	s_add_u32 s8, s8, s10
	s_addc_u32 s9, s9, s11
	v_mul_f32_e32 v9, v5, v7
	v_mul_f32_e32 v10, v5, v6
	v_fma_f32 v9, v4, v6, -v9
	v_fma_f32 v10, v4, v7, v10
	v_add_f32_e32 v6, v9, v48
	v_add_f32_e32 v7, v10, v49
	v_cvt_pk_bf16_f32 v8, v6, v7
	global_store_dword v2, v8, s[8:9]
	s_add_u32 s8, s8, s10
	s_addc_u32 s9, s9, s11
	v_mul_f32_e32 v9, v5, v7
	v_mul_f32_e32 v10, v5, v6
	v_fma_f32 v9, v4, v6, -v9
	v_fma_f32 v10, v4, v7, v10
	v_add_f32_e32 v6, v9, v50
	v_add_f32_e32 v7, v10, v51
	v_cvt_pk_bf16_f32 v8, v6, v7
	global_store_dword v2, v8, s[8:9]
	s_add_u32 s8, s8, s10
	s_addc_u32 s9, s9, s11
	v_mul_f32_e32 v9, v5, v7
	v_mul_f32_e32 v10, v5, v6
	v_fma_f32 v9, v4, v6, -v9
	v_fma_f32 v10, v4, v7, v10
	v_add_f32_e32 v6, v9, v52
	v_add_f32_e32 v7, v10, v53
	v_cvt_pk_bf16_f32 v8, v6, v7
	global_store_dword v2, v8, s[8:9]
	s_add_u32 s8, s8, s10
	s_addc_u32 s9, s9, s11
	v_mul_f32_e32 v9, v5, v7
	v_mul_f32_e32 v10, v5, v6
	v_fma_f32 v9, v4, v6, -v9
	v_fma_f32 v10, v4, v7, v10
	v_add_f32_e32 v6, v9, v54
	v_add_f32_e32 v7, v10, v55
	v_cvt_pk_bf16_f32 v8, v6, v7
	global_store_dword v2, v8, s[8:9]
	s_add_u32 s8, s8, s10
	s_addc_u32 s9, s9, s11
	v_mul_f32_e32 v9, v5, v7
	v_mul_f32_e32 v10, v5, v6
	v_fma_f32 v9, v4, v6, -v9
	v_fma_f32 v10, v4, v7, v10
	v_add_f32_e32 v6, v9, v56
	v_add_f32_e32 v7, v10, v57
	v_cvt_pk_bf16_f32 v8, v6, v7
	global_store_dword v2, v8, s[8:9]
	s_add_u32 s8, s8, s10
	s_addc_u32 s9, s9, s11
	v_mul_f32_e32 v9, v5, v7
	v_mul_f32_e32 v10, v5, v6
	v_fma_f32 v9, v4, v6, -v9
	v_fma_f32 v10, v4, v7, v10
	v_add_f32_e32 v6, v9, v58
	v_add_f32_e32 v7, v10, v59
	v_cvt_pk_bf16_f32 v8, v6, v7
	global_store_dword v2, v8, s[8:9]
	s_add_u32 s8, s8, s10
	s_addc_u32 s9, s9, s11
	v_mul_f32_e32 v9, v5, v7
	v_mul_f32_e32 v10, v5, v6
	v_fma_f32 v9, v4, v6, -v9
	v_fma_f32 v10, v4, v7, v10
	v_add_f32_e32 v6, v9, v60
	v_add_f32_e32 v7, v10, v61
	v_cvt_pk_bf16_f32 v8, v6, v7
	global_store_dword v2, v8, s[8:9]
	s_add_u32 s8, s8, s10
	s_addc_u32 s9, s9, s11
	v_mul_f32_e32 v9, v5, v7
	v_mul_f32_e32 v10, v5, v6
	v_fma_f32 v9, v4, v6, -v9
	v_fma_f32 v10, v4, v7, v10
	v_add_f32_e32 v6, v9, v62
	v_add_f32_e32 v7, v10, v63
	global_load_dwordx2 v[96:97], v1, s[0:1]
	s_add_u32 s0, s0, s10
	s_addc_u32 s1, s1, s11
	global_load_dwordx2 v[98:99], v1, s[0:1]
	s_add_u32 s0, s0, s10
	s_addc_u32 s1, s1, s11
	global_load_dwordx2 v[100:101], v1, s[0:1]
	s_add_u32 s0, s0, s10
	s_addc_u32 s1, s1, s11
	global_load_dwordx2 v[102:103], v1, s[0:1]
	s_add_u32 s0, s0, s10
	s_addc_u32 s1, s1, s11
	global_load_dwordx2 v[104:105], v1, s[0:1]
	s_add_u32 s0, s0, s10
	s_addc_u32 s1, s1, s11
	global_load_dwordx2 v[106:107], v1, s[0:1]
	s_add_u32 s0, s0, s10
	s_addc_u32 s1, s1, s11
	global_load_dwordx2 v[108:109], v1, s[0:1]
	s_add_u32 s0, s0, s10
	s_addc_u32 s1, s1, s11
	global_load_dwordx2 v[110:111], v1, s[0:1]
	s_add_u32 s0, s0, s10
	s_addc_u32 s1, s1, s11
	global_load_dwordx2 v[112:113], v1, s[0:1]
	s_add_u32 s0, s0, s10
	s_addc_u32 s1, s1, s11
	global_load_dwordx2 v[114:115], v1, s[0:1]
	s_add_u32 s0, s0, s10
	s_addc_u32 s1, s1, s11
	global_load_dwordx2 v[116:117], v1, s[0:1]
	s_add_u32 s0, s0, s10
	s_addc_u32 s1, s1, s11
	global_load_dwordx2 v[118:119], v1, s[0:1]
	s_add_u32 s0, s0, s10
	s_addc_u32 s1, s1, s11
	global_load_dwordx2 v[120:121], v1, s[0:1]
	s_add_u32 s0, s0, s10
	s_addc_u32 s1, s1, s11
	global_load_dwordx2 v[122:123], v1, s[0:1]
	s_add_u32 s0, s0, s10
	s_addc_u32 s1, s1, s11
	global_load_dwordx2 v[124:125], v1, s[0:1]
	s_add_u32 s0, s0, s10
	s_addc_u32 s1, s1, s11
	global_load_dwordx2 v[126:127], v1, s[0:1]
	s_add_u32 s0, s0, s10
	s_addc_u32 s1, s1, s11
	s_waitcnt vmcnt(34)
	v_cvt_pk_bf16_f32 v8, v6, v7
	global_store_dword v2, v8, s[8:9]
	s_add_u32 s8, s8, s10
	s_addc_u32 s9, s9, s11
	v_mul_f32_e32 v9, v5, v7
	v_mul_f32_e32 v10, v5, v6
	v_fma_f32 v9, v4, v6, -v9
	v_fma_f32 v10, v4, v7, v10
	v_add_f32_e32 v6, v9, v64
	v_add_f32_e32 v7, v10, v65
	v_cvt_pk_bf16_f32 v8, v6, v7
	global_store_dword v2, v8, s[8:9]
	s_add_u32 s8, s8, s10
	s_addc_u32 s9, s9, s11
	v_mul_f32_e32 v9, v5, v7
	v_mul_f32_e32 v10, v5, v6
	v_fma_f32 v9, v4, v6, -v9
	v_fma_f32 v10, v4, v7, v10
	v_add_f32_e32 v6, v9, v66
	v_add_f32_e32 v7, v10, v67
	v_cvt_pk_bf16_f32 v8, v6, v7
	global_store_dword v2, v8, s[8:9]
	s_add_u32 s8, s8, s10
	s_addc_u32 s9, s9, s11
	v_mul_f32_e32 v9, v5, v7
	v_mul_f32_e32 v10, v5, v6
	v_fma_f32 v9, v4, v6, -v9
	v_fma_f32 v10, v4, v7, v10
	v_add_f32_e32 v6, v9, v68
	v_add_f32_e32 v7, v10, v69
	v_cvt_pk_bf16_f32 v8, v6, v7
	global_store_dword v2, v8, s[8:9]
	s_add_u32 s8, s8, s10
	s_addc_u32 s9, s9, s11
	v_mul_f32_e32 v9, v5, v7
	v_mul_f32_e32 v10, v5, v6
	v_fma_f32 v9, v4, v6, -v9
	v_fma_f32 v10, v4, v7, v10
	v_add_f32_e32 v6, v9, v70
	v_add_f32_e32 v7, v10, v71
	v_cvt_pk_bf16_f32 v8, v6, v7
	global_store_dword v2, v8, s[8:9]
	s_add_u32 s8, s8, s10
	s_addc_u32 s9, s9, s11
	v_mul_f32_e32 v9, v5, v7
	v_mul_f32_e32 v10, v5, v6
	v_fma_f32 v9, v4, v6, -v9
	v_fma_f32 v10, v4, v7, v10
	v_add_f32_e32 v6, v9, v72
	v_add_f32_e32 v7, v10, v73
	v_cvt_pk_bf16_f32 v8, v6, v7
	global_store_dword v2, v8, s[8:9]
	s_add_u32 s8, s8, s10
	s_addc_u32 s9, s9, s11
	v_mul_f32_e32 v9, v5, v7
	v_mul_f32_e32 v10, v5, v6
	v_fma_f32 v9, v4, v6, -v9
	v_fma_f32 v10, v4, v7, v10
	v_add_f32_e32 v6, v9, v74
	v_add_f32_e32 v7, v10, v75
	v_cvt_pk_bf16_f32 v8, v6, v7
	global_store_dword v2, v8, s[8:9]
	s_add_u32 s8, s8, s10
	s_addc_u32 s9, s9, s11
	v_mul_f32_e32 v9, v5, v7
	v_mul_f32_e32 v10, v5, v6
	v_fma_f32 v9, v4, v6, -v9
	v_fma_f32 v10, v4, v7, v10
	v_add_f32_e32 v6, v9, v76
	v_add_f32_e32 v7, v10, v77
	v_cvt_pk_bf16_f32 v8, v6, v7
	global_store_dword v2, v8, s[8:9]
	s_add_u32 s8, s8, s10
	s_addc_u32 s9, s9, s11
	v_mul_f32_e32 v9, v5, v7
	v_mul_f32_e32 v10, v5, v6
	v_fma_f32 v9, v4, v6, -v9
	v_fma_f32 v10, v4, v7, v10
	v_add_f32_e32 v6, v9, v78
	v_add_f32_e32 v7, v10, v79
	v_cvt_pk_bf16_f32 v8, v6, v7
	global_store_dword v2, v8, s[8:9]
	s_add_u32 s8, s8, s10
	s_addc_u32 s9, s9, s11
	v_mul_f32_e32 v9, v5, v7
	v_mul_f32_e32 v10, v5, v6
	v_fma_f32 v9, v4, v6, -v9
	v_fma_f32 v10, v4, v7, v10
	v_add_f32_e32 v6, v9, v80
	v_add_f32_e32 v7, v10, v81
	v_cvt_pk_bf16_f32 v8, v6, v7
	global_store_dword v2, v8, s[8:9]
	s_add_u32 s8, s8, s10
	s_addc_u32 s9, s9, s11
	v_mul_f32_e32 v9, v5, v7
	v_mul_f32_e32 v10, v5, v6
	v_fma_f32 v9, v4, v6, -v9
	v_fma_f32 v10, v4, v7, v10
	v_add_f32_e32 v6, v9, v82
	v_add_f32_e32 v7, v10, v83
	v_cvt_pk_bf16_f32 v8, v6, v7
	global_store_dword v2, v8, s[8:9]
	s_add_u32 s8, s8, s10
	s_addc_u32 s9, s9, s11
	v_mul_f32_e32 v9, v5, v7
	v_mul_f32_e32 v10, v5, v6
	v_fma_f32 v9, v4, v6, -v9
	v_fma_f32 v10, v4, v7, v10
	v_add_f32_e32 v6, v9, v84
	v_add_f32_e32 v7, v10, v85
	v_cvt_pk_bf16_f32 v8, v6, v7
	global_store_dword v2, v8, s[8:9]
	s_add_u32 s8, s8, s10
	s_addc_u32 s9, s9, s11
	v_mul_f32_e32 v9, v5, v7
	v_mul_f32_e32 v10, v5, v6
	v_fma_f32 v9, v4, v6, -v9
	v_fma_f32 v10, v4, v7, v10
	v_add_f32_e32 v6, v9, v86
	v_add_f32_e32 v7, v10, v87
	v_cvt_pk_bf16_f32 v8, v6, v7
	global_store_dword v2, v8, s[8:9]
	s_add_u32 s8, s8, s10
	s_addc_u32 s9, s9, s11
	v_mul_f32_e32 v9, v5, v7
	v_mul_f32_e32 v10, v5, v6
	v_fma_f32 v9, v4, v6, -v9
	v_fma_f32 v10, v4, v7, v10
	v_add_f32_e32 v6, v9, v88
	v_add_f32_e32 v7, v10, v89
	v_cvt_pk_bf16_f32 v8, v6, v7
	global_store_dword v2, v8, s[8:9]
	s_add_u32 s8, s8, s10
	s_addc_u32 s9, s9, s11
	v_mul_f32_e32 v9, v5, v7
	v_mul_f32_e32 v10, v5, v6
	v_fma_f32 v9, v4, v6, -v9
	v_fma_f32 v10, v4, v7, v10
	v_add_f32_e32 v6, v9, v90
	v_add_f32_e32 v7, v10, v91
	v_cvt_pk_bf16_f32 v8, v6, v7
	global_store_dword v2, v8, s[8:9]
	s_add_u32 s8, s8, s10
	s_addc_u32 s9, s9, s11
	v_mul_f32_e32 v9, v5, v7
	v_mul_f32_e32 v10, v5, v6
	v_fma_f32 v9, v4, v6, -v9
	v_fma_f32 v10, v4, v7, v10
	v_add_f32_e32 v6, v9, v92
	v_add_f32_e32 v7, v10, v93
	v_cvt_pk_bf16_f32 v8, v6, v7
	global_store_dword v2, v8, s[8:9]
	s_add_u32 s8, s8, s10
	s_addc_u32 s9, s9, s11
	v_mul_f32_e32 v9, v5, v7
	v_mul_f32_e32 v10, v5, v6
	v_fma_f32 v9, v4, v6, -v9
	v_fma_f32 v10, v4, v7, v10
	v_add_f32_e32 v6, v9, v94
	v_add_f32_e32 v7, v10, v95
	global_load_dwordx2 v[32:33], v1, s[0:1]
	s_add_u32 s0, s0, s10
	s_addc_u32 s1, s1, s11
	global_load_dwordx2 v[34:35], v1, s[0:1]
	s_add_u32 s0, s0, s10
	s_addc_u32 s1, s1, s11
	global_load_dwordx2 v[36:37], v1, s[0:1]
	s_add_u32 s0, s0, s10
	s_addc_u32 s1, s1, s11
	global_load_dwordx2 v[38:39], v1, s[0:1]
	s_add_u32 s0, s0, s10
	s_addc_u32 s1, s1, s11
	global_load_dwordx2 v[40:41], v1, s[0:1]
	s_add_u32 s0, s0, s10
	s_addc_u32 s1, s1, s11
	global_load_dwordx2 v[42:43], v1, s[0:1]
	s_add_u32 s0, s0, s10
	s_addc_u32 s1, s1, s11
	global_load_dwordx2 v[44:45], v1, s[0:1]
	s_add_u32 s0, s0, s10
	s_addc_u32 s1, s1, s11
	global_load_dwordx2 v[46:47], v1, s[0:1]
	s_add_u32 s0, s0, s10
	s_addc_u32 s1, s1, s11
	global_load_dwordx2 v[48:49], v1, s[0:1]
	s_add_u32 s0, s0, s10
	s_addc_u32 s1, s1, s11
	global_load_dwordx2 v[50:51], v1, s[0:1]
	s_add_u32 s0, s0, s10
	s_addc_u32 s1, s1, s11
	global_load_dwordx2 v[52:53], v1, s[0:1]
	s_add_u32 s0, s0, s10
	s_addc_u32 s1, s1, s11
	global_load_dwordx2 v[54:55], v1, s[0:1]
	s_add_u32 s0, s0, s10
	s_addc_u32 s1, s1, s11
	global_load_dwordx2 v[56:57], v1, s[0:1]
	s_add_u32 s0, s0, s10
	s_addc_u32 s1, s1, s11
	global_load_dwordx2 v[58:59], v1, s[0:1]
	s_add_u32 s0, s0, s10
	s_addc_u32 s1, s1, s11
	global_load_dwordx2 v[60:61], v1, s[0:1]
	s_add_u32 s0, s0, s10
	s_addc_u32 s1, s1, s11
	global_load_dwordx2 v[62:63], v1, s[0:1]
	s_add_u32 s0, s0, s10
	s_addc_u32 s1, s1, s11
	s_waitcnt vmcnt(32)
	v_cvt_pk_bf16_f32 v8, v6, v7
	global_store_dword v2, v8, s[8:9]
	s_add_u32 s8, s8, s10
	s_addc_u32 s9, s9, s11
	v_mul_f32_e32 v9, v5, v7
	v_mul_f32_e32 v10, v5, v6
	v_fma_f32 v9, v4, v6, -v9
	v_fma_f32 v10, v4, v7, v10
	v_add_f32_e32 v6, v9, v96
	v_add_f32_e32 v7, v10, v97
	v_cvt_pk_bf16_f32 v8, v6, v7
	global_store_dword v2, v8, s[8:9]
	s_add_u32 s8, s8, s10
	s_addc_u32 s9, s9, s11
	v_mul_f32_e32 v9, v5, v7
	v_mul_f32_e32 v10, v5, v6
	v_fma_f32 v9, v4, v6, -v9
	v_fma_f32 v10, v4, v7, v10
	v_add_f32_e32 v6, v9, v98
	v_add_f32_e32 v7, v10, v99
	v_cvt_pk_bf16_f32 v8, v6, v7
	global_store_dword v2, v8, s[8:9]
	s_add_u32 s8, s8, s10
	s_addc_u32 s9, s9, s11
	v_mul_f32_e32 v9, v5, v7
	v_mul_f32_e32 v10, v5, v6
	v_fma_f32 v9, v4, v6, -v9
	v_fma_f32 v10, v4, v7, v10
	v_add_f32_e32 v6, v9, v100
	v_add_f32_e32 v7, v10, v101
	v_cvt_pk_bf16_f32 v8, v6, v7
	global_store_dword v2, v8, s[8:9]
	s_add_u32 s8, s8, s10
	s_addc_u32 s9, s9, s11
	v_mul_f32_e32 v9, v5, v7
	v_mul_f32_e32 v10, v5, v6
	v_fma_f32 v9, v4, v6, -v9
	v_fma_f32 v10, v4, v7, v10
	v_add_f32_e32 v6, v9, v102
	v_add_f32_e32 v7, v10, v103
	v_cvt_pk_bf16_f32 v8, v6, v7
	global_store_dword v2, v8, s[8:9]
	s_add_u32 s8, s8, s10
	s_addc_u32 s9, s9, s11
	v_mul_f32_e32 v9, v5, v7
	v_mul_f32_e32 v10, v5, v6
	v_fma_f32 v9, v4, v6, -v9
	v_fma_f32 v10, v4, v7, v10
	v_add_f32_e32 v6, v9, v104
	v_add_f32_e32 v7, v10, v105
	v_cvt_pk_bf16_f32 v8, v6, v7
	global_store_dword v2, v8, s[8:9]
	s_add_u32 s8, s8, s10
	s_addc_u32 s9, s9, s11
	v_mul_f32_e32 v9, v5, v7
	v_mul_f32_e32 v10, v5, v6
	v_fma_f32 v9, v4, v6, -v9
	v_fma_f32 v10, v4, v7, v10
	v_add_f32_e32 v6, v9, v106
	v_add_f32_e32 v7, v10, v107
	v_cvt_pk_bf16_f32 v8, v6, v7
	global_store_dword v2, v8, s[8:9]
	s_add_u32 s8, s8, s10
	s_addc_u32 s9, s9, s11
	v_mul_f32_e32 v9, v5, v7
	v_mul_f32_e32 v10, v5, v6
	v_fma_f32 v9, v4, v6, -v9
	v_fma_f32 v10, v4, v7, v10
	v_add_f32_e32 v6, v9, v108
	v_add_f32_e32 v7, v10, v109
	v_cvt_pk_bf16_f32 v8, v6, v7
	global_store_dword v2, v8, s[8:9]
	s_add_u32 s8, s8, s10
	s_addc_u32 s9, s9, s11
	v_mul_f32_e32 v9, v5, v7
	v_mul_f32_e32 v10, v5, v6
	v_fma_f32 v9, v4, v6, -v9
	v_fma_f32 v10, v4, v7, v10
	v_add_f32_e32 v6, v9, v110
	v_add_f32_e32 v7, v10, v111
	v_cvt_pk_bf16_f32 v8, v6, v7
	global_store_dword v2, v8, s[8:9]
	s_add_u32 s8, s8, s10
	s_addc_u32 s9, s9, s11
	v_mul_f32_e32 v9, v5, v7
	v_mul_f32_e32 v10, v5, v6
	v_fma_f32 v9, v4, v6, -v9
	v_fma_f32 v10, v4, v7, v10
	v_add_f32_e32 v6, v9, v112
	v_add_f32_e32 v7, v10, v113
	v_cvt_pk_bf16_f32 v8, v6, v7
	global_store_dword v2, v8, s[8:9]
	s_add_u32 s8, s8, s10
	s_addc_u32 s9, s9, s11
	v_mul_f32_e32 v9, v5, v7
	v_mul_f32_e32 v10, v5, v6
	v_fma_f32 v9, v4, v6, -v9
	v_fma_f32 v10, v4, v7, v10
	v_add_f32_e32 v6, v9, v114
	v_add_f32_e32 v7, v10, v115
	v_cvt_pk_bf16_f32 v8, v6, v7
	global_store_dword v2, v8, s[8:9]
	s_add_u32 s8, s8, s10
	s_addc_u32 s9, s9, s11
	v_mul_f32_e32 v9, v5, v7
	v_mul_f32_e32 v10, v5, v6
	v_fma_f32 v9, v4, v6, -v9
	v_fma_f32 v10, v4, v7, v10
	v_add_f32_e32 v6, v9, v116
	v_add_f32_e32 v7, v10, v117
	v_cvt_pk_bf16_f32 v8, v6, v7
	global_store_dword v2, v8, s[8:9]
	s_add_u32 s8, s8, s10
	s_addc_u32 s9, s9, s11
	v_mul_f32_e32 v9, v5, v7
	v_mul_f32_e32 v10, v5, v6
	v_fma_f32 v9, v4, v6, -v9
	v_fma_f32 v10, v4, v7, v10
	v_add_f32_e32 v6, v9, v118
	v_add_f32_e32 v7, v10, v119
	v_cvt_pk_bf16_f32 v8, v6, v7
	global_store_dword v2, v8, s[8:9]
	s_add_u32 s8, s8, s10
	s_addc_u32 s9, s9, s11
	v_mul_f32_e32 v9, v5, v7
	v_mul_f32_e32 v10, v5, v6
	v_fma_f32 v9, v4, v6, -v9
	v_fma_f32 v10, v4, v7, v10
	v_add_f32_e32 v6, v9, v120
	v_add_f32_e32 v7, v10, v121
	v_cvt_pk_bf16_f32 v8, v6, v7
	global_store_dword v2, v8, s[8:9]
	s_add_u32 s8, s8, s10
	s_addc_u32 s9, s9, s11
	v_mul_f32_e32 v9, v5, v7
	v_mul_f32_e32 v10, v5, v6
	v_fma_f32 v9, v4, v6, -v9
	v_fma_f32 v10, v4, v7, v10
	v_add_f32_e32 v6, v9, v122
	v_add_f32_e32 v7, v10, v123
	v_cvt_pk_bf16_f32 v8, v6, v7
	global_store_dword v2, v8, s[8:9]
	s_add_u32 s8, s8, s10
	s_addc_u32 s9, s9, s11
	v_mul_f32_e32 v9, v5, v7
	v_mul_f32_e32 v10, v5, v6
	v_fma_f32 v9, v4, v6, -v9
	v_fma_f32 v10, v4, v7, v10
	v_add_f32_e32 v6, v9, v124
	v_add_f32_e32 v7, v10, v125
	v_cvt_pk_bf16_f32 v8, v6, v7
	global_store_dword v2, v8, s[8:9]
	s_add_u32 s8, s8, s10
	s_addc_u32 s9, s9, s11
	v_mul_f32_e32 v9, v5, v7
	v_mul_f32_e32 v10, v5, v6
	v_fma_f32 v9, v4, v6, -v9
	v_fma_f32 v10, v4, v7, v10
	v_add_f32_e32 v6, v9, v126
	v_add_f32_e32 v7, v10, v127
	global_load_dwordx2 v[64:65], v1, s[0:1]
	s_add_u32 s0, s0, s10
	s_addc_u32 s1, s1, s11
	global_load_dwordx2 v[66:67], v1, s[0:1]
	s_add_u32 s0, s0, s10
	s_addc_u32 s1, s1, s11
	global_load_dwordx2 v[68:69], v1, s[0:1]
	s_add_u32 s0, s0, s10
	s_addc_u32 s1, s1, s11
	global_load_dwordx2 v[70:71], v1, s[0:1]
	s_add_u32 s0, s0, s10
	s_addc_u32 s1, s1, s11
	global_load_dwordx2 v[72:73], v1, s[0:1]
	s_add_u32 s0, s0, s10
	s_addc_u32 s1, s1, s11
	global_load_dwordx2 v[74:75], v1, s[0:1]
	s_add_u32 s0, s0, s10
	s_addc_u32 s1, s1, s11
	global_load_dwordx2 v[76:77], v1, s[0:1]
	s_add_u32 s0, s0, s10
	s_addc_u32 s1, s1, s11
	global_load_dwordx2 v[78:79], v1, s[0:1]
	s_add_u32 s0, s0, s10
	s_addc_u32 s1, s1, s11
	global_load_dwordx2 v[80:81], v1, s[0:1]
	s_add_u32 s0, s0, s10
	s_addc_u32 s1, s1, s11
	global_load_dwordx2 v[82:83], v1, s[0:1]
	s_add_u32 s0, s0, s10
	s_addc_u32 s1, s1, s11
	global_load_dwordx2 v[84:85], v1, s[0:1]
	s_add_u32 s0, s0, s10
	s_addc_u32 s1, s1, s11
	global_load_dwordx2 v[86:87], v1, s[0:1]
	s_add_u32 s0, s0, s10
	s_addc_u32 s1, s1, s11
	global_load_dwordx2 v[88:89], v1, s[0:1]
	s_add_u32 s0, s0, s10
	s_addc_u32 s1, s1, s11
	global_load_dwordx2 v[90:91], v1, s[0:1]
	s_add_u32 s0, s0, s10
	s_addc_u32 s1, s1, s11
	global_load_dwordx2 v[92:93], v1, s[0:1]
	s_add_u32 s0, s0, s10
	s_addc_u32 s1, s1, s11
	global_load_dwordx2 v[94:95], v1, s[0:1]
	s_add_u32 s0, s0, s10
	s_addc_u32 s1, s1, s11
	s_waitcnt vmcnt(32)
	v_cvt_pk_bf16_f32 v8, v6, v7
	global_store_dword v2, v8, s[8:9]
	s_add_u32 s8, s8, s10
	s_addc_u32 s9, s9, s11
	v_mul_f32_e32 v9, v5, v7
	v_mul_f32_e32 v10, v5, v6
	v_fma_f32 v9, v4, v6, -v9
	v_fma_f32 v10, v4, v7, v10
	v_add_f32_e32 v6, v9, v32
	v_add_f32_e32 v7, v10, v33
	v_cvt_pk_bf16_f32 v8, v6, v7
	global_store_dword v2, v8, s[8:9]
	s_add_u32 s8, s8, s10
	s_addc_u32 s9, s9, s11
	v_mul_f32_e32 v9, v5, v7
	v_mul_f32_e32 v10, v5, v6
	v_fma_f32 v9, v4, v6, -v9
	v_fma_f32 v10, v4, v7, v10
	v_add_f32_e32 v6, v9, v34
	v_add_f32_e32 v7, v10, v35
	v_cvt_pk_bf16_f32 v8, v6, v7
	global_store_dword v2, v8, s[8:9]
	s_add_u32 s8, s8, s10
	s_addc_u32 s9, s9, s11
	v_mul_f32_e32 v9, v5, v7
	v_mul_f32_e32 v10, v5, v6
	v_fma_f32 v9, v4, v6, -v9
	v_fma_f32 v10, v4, v7, v10
	v_add_f32_e32 v6, v9, v36
	v_add_f32_e32 v7, v10, v37
	v_cvt_pk_bf16_f32 v8, v6, v7
	global_store_dword v2, v8, s[8:9]
	s_add_u32 s8, s8, s10
	s_addc_u32 s9, s9, s11
	v_mul_f32_e32 v9, v5, v7
	v_mul_f32_e32 v10, v5, v6
	v_fma_f32 v9, v4, v6, -v9
	v_fma_f32 v10, v4, v7, v10
	v_add_f32_e32 v6, v9, v38
	v_add_f32_e32 v7, v10, v39
	v_cvt_pk_bf16_f32 v8, v6, v7
	global_store_dword v2, v8, s[8:9]
	s_add_u32 s8, s8, s10
	s_addc_u32 s9, s9, s11
	v_mul_f32_e32 v9, v5, v7
	v_mul_f32_e32 v10, v5, v6
	v_fma_f32 v9, v4, v6, -v9
	v_fma_f32 v10, v4, v7, v10
	v_add_f32_e32 v6, v9, v40
	v_add_f32_e32 v7, v10, v41
	v_cvt_pk_bf16_f32 v8, v6, v7
	global_store_dword v2, v8, s[8:9]
	s_add_u32 s8, s8, s10
	s_addc_u32 s9, s9, s11
	v_mul_f32_e32 v9, v5, v7
	v_mul_f32_e32 v10, v5, v6
	v_fma_f32 v9, v4, v6, -v9
	v_fma_f32 v10, v4, v7, v10
	v_add_f32_e32 v6, v9, v42
	v_add_f32_e32 v7, v10, v43
	v_cvt_pk_bf16_f32 v8, v6, v7
	global_store_dword v2, v8, s[8:9]
	s_add_u32 s8, s8, s10
	s_addc_u32 s9, s9, s11
	v_mul_f32_e32 v9, v5, v7
	v_mul_f32_e32 v10, v5, v6
	v_fma_f32 v9, v4, v6, -v9
	v_fma_f32 v10, v4, v7, v10
	v_add_f32_e32 v6, v9, v44
	v_add_f32_e32 v7, v10, v45
	v_cvt_pk_bf16_f32 v8, v6, v7
	global_store_dword v2, v8, s[8:9]
	s_add_u32 s8, s8, s10
	s_addc_u32 s9, s9, s11
	v_mul_f32_e32 v9, v5, v7
	v_mul_f32_e32 v10, v5, v6
	v_fma_f32 v9, v4, v6, -v9
	v_fma_f32 v10, v4, v7, v10
	v_add_f32_e32 v6, v9, v46
	v_add_f32_e32 v7, v10, v47
	v_cvt_pk_bf16_f32 v8, v6, v7
	global_store_dword v2, v8, s[8:9]
	s_add_u32 s8, s8, s10
	s_addc_u32 s9, s9, s11
	v_mul_f32_e32 v9, v5, v7
	v_mul_f32_e32 v10, v5, v6
	v_fma_f32 v9, v4, v6, -v9
	v_fma_f32 v10, v4, v7, v10
	v_add_f32_e32 v6, v9, v48
	v_add_f32_e32 v7, v10, v49
	v_cvt_pk_bf16_f32 v8, v6, v7
	global_store_dword v2, v8, s[8:9]
	s_add_u32 s8, s8, s10
	s_addc_u32 s9, s9, s11
	v_mul_f32_e32 v9, v5, v7
	v_mul_f32_e32 v10, v5, v6
	v_fma_f32 v9, v4, v6, -v9
	v_fma_f32 v10, v4, v7, v10
	v_add_f32_e32 v6, v9, v50
	v_add_f32_e32 v7, v10, v51
	v_cvt_pk_bf16_f32 v8, v6, v7
	global_store_dword v2, v8, s[8:9]
	s_add_u32 s8, s8, s10
	s_addc_u32 s9, s9, s11
	v_mul_f32_e32 v9, v5, v7
	v_mul_f32_e32 v10, v5, v6
	v_fma_f32 v9, v4, v6, -v9
	v_fma_f32 v10, v4, v7, v10
	v_add_f32_e32 v6, v9, v52
	v_add_f32_e32 v7, v10, v53
	v_cvt_pk_bf16_f32 v8, v6, v7
	global_store_dword v2, v8, s[8:9]
	s_add_u32 s8, s8, s10
	s_addc_u32 s9, s9, s11
	v_mul_f32_e32 v9, v5, v7
	v_mul_f32_e32 v10, v5, v6
	v_fma_f32 v9, v4, v6, -v9
	v_fma_f32 v10, v4, v7, v10
	v_add_f32_e32 v6, v9, v54
	v_add_f32_e32 v7, v10, v55
	v_cvt_pk_bf16_f32 v8, v6, v7
	global_store_dword v2, v8, s[8:9]
	s_add_u32 s8, s8, s10
	s_addc_u32 s9, s9, s11
	v_mul_f32_e32 v9, v5, v7
	v_mul_f32_e32 v10, v5, v6
	v_fma_f32 v9, v4, v6, -v9
	v_fma_f32 v10, v4, v7, v10
	v_add_f32_e32 v6, v9, v56
	v_add_f32_e32 v7, v10, v57
	v_cvt_pk_bf16_f32 v8, v6, v7
	global_store_dword v2, v8, s[8:9]
	s_add_u32 s8, s8, s10
	s_addc_u32 s9, s9, s11
	v_mul_f32_e32 v9, v5, v7
	v_mul_f32_e32 v10, v5, v6
	v_fma_f32 v9, v4, v6, -v9
	v_fma_f32 v10, v4, v7, v10
	v_add_f32_e32 v6, v9, v58
	v_add_f32_e32 v7, v10, v59
	v_cvt_pk_bf16_f32 v8, v6, v7
	global_store_dword v2, v8, s[8:9]
	s_add_u32 s8, s8, s10
	s_addc_u32 s9, s9, s11
	v_mul_f32_e32 v9, v5, v7
	v_mul_f32_e32 v10, v5, v6
	v_fma_f32 v9, v4, v6, -v9
	v_fma_f32 v10, v4, v7, v10
	v_add_f32_e32 v6, v9, v60
	v_add_f32_e32 v7, v10, v61
	v_cvt_pk_bf16_f32 v8, v6, v7
	global_store_dword v2, v8, s[8:9]
	s_add_u32 s8, s8, s10
	s_addc_u32 s9, s9, s11
	v_mul_f32_e32 v9, v5, v7
	v_mul_f32_e32 v10, v5, v6
	v_fma_f32 v9, v4, v6, -v9
	v_fma_f32 v10, v4, v7, v10
	v_add_f32_e32 v6, v9, v62
	v_add_f32_e32 v7, v10, v63
	global_load_dwordx2 v[96:97], v1, s[0:1]
	s_add_u32 s0, s0, s10
	s_addc_u32 s1, s1, s11
	global_load_dwordx2 v[98:99], v1, s[0:1]
	s_add_u32 s0, s0, s10
	s_addc_u32 s1, s1, s11
	global_load_dwordx2 v[100:101], v1, s[0:1]
	s_add_u32 s0, s0, s10
	s_addc_u32 s1, s1, s11
	global_load_dwordx2 v[102:103], v1, s[0:1]
	s_add_u32 s0, s0, s10
	s_addc_u32 s1, s1, s11
	global_load_dwordx2 v[104:105], v1, s[0:1]
	s_add_u32 s0, s0, s10
	s_addc_u32 s1, s1, s11
	global_load_dwordx2 v[106:107], v1, s[0:1]
	s_add_u32 s0, s0, s10
	s_addc_u32 s1, s1, s11
	global_load_dwordx2 v[108:109], v1, s[0:1]
	s_add_u32 s0, s0, s10
	s_addc_u32 s1, s1, s11
	global_load_dwordx2 v[110:111], v1, s[0:1]
	s_add_u32 s0, s0, s10
	s_addc_u32 s1, s1, s11
	global_load_dwordx2 v[112:113], v1, s[0:1]
	s_add_u32 s0, s0, s10
	s_addc_u32 s1, s1, s11
	global_load_dwordx2 v[114:115], v1, s[0:1]
	s_add_u32 s0, s0, s10
	s_addc_u32 s1, s1, s11
	global_load_dwordx2 v[116:117], v1, s[0:1]
	s_add_u32 s0, s0, s10
	s_addc_u32 s1, s1, s11
	global_load_dwordx2 v[118:119], v1, s[0:1]
	s_add_u32 s0, s0, s10
	s_addc_u32 s1, s1, s11
	global_load_dwordx2 v[120:121], v1, s[0:1]
	s_add_u32 s0, s0, s10
	s_addc_u32 s1, s1, s11
	global_load_dwordx2 v[122:123], v1, s[0:1]
	s_add_u32 s0, s0, s10
	s_addc_u32 s1, s1, s11
	global_load_dwordx2 v[124:125], v1, s[0:1]
	s_add_u32 s0, s0, s10
	s_addc_u32 s1, s1, s11
	global_load_dwordx2 v[126:127], v1, s[0:1]
	s_add_u32 s0, s0, s10
	s_addc_u32 s1, s1, s11
	s_waitcnt vmcnt(32)
	v_cvt_pk_bf16_f32 v8, v6, v7
	global_store_dword v2, v8, s[8:9]
	s_add_u32 s8, s8, s10
	s_addc_u32 s9, s9, s11
	v_mul_f32_e32 v9, v5, v7
	v_mul_f32_e32 v10, v5, v6
	v_fma_f32 v9, v4, v6, -v9
	v_fma_f32 v10, v4, v7, v10
	v_add_f32_e32 v6, v9, v64
	v_add_f32_e32 v7, v10, v65
	v_cvt_pk_bf16_f32 v8, v6, v7
	global_store_dword v2, v8, s[8:9]
	s_add_u32 s8, s8, s10
	s_addc_u32 s9, s9, s11
	v_mul_f32_e32 v9, v5, v7
	v_mul_f32_e32 v10, v5, v6
	v_fma_f32 v9, v4, v6, -v9
	v_fma_f32 v10, v4, v7, v10
	v_add_f32_e32 v6, v9, v66
	v_add_f32_e32 v7, v10, v67
	v_cvt_pk_bf16_f32 v8, v6, v7
	global_store_dword v2, v8, s[8:9]
	s_add_u32 s8, s8, s10
	s_addc_u32 s9, s9, s11
	v_mul_f32_e32 v9, v5, v7
	v_mul_f32_e32 v10, v5, v6
	v_fma_f32 v9, v4, v6, -v9
	v_fma_f32 v10, v4, v7, v10
	v_add_f32_e32 v6, v9, v68
	v_add_f32_e32 v7, v10, v69
	v_cvt_pk_bf16_f32 v8, v6, v7
	global_store_dword v2, v8, s[8:9]
	s_add_u32 s8, s8, s10
	s_addc_u32 s9, s9, s11
	v_mul_f32_e32 v9, v5, v7
	v_mul_f32_e32 v10, v5, v6
	v_fma_f32 v9, v4, v6, -v9
	v_fma_f32 v10, v4, v7, v10
	v_add_f32_e32 v6, v9, v70
	v_add_f32_e32 v7, v10, v71
	v_cvt_pk_bf16_f32 v8, v6, v7
	global_store_dword v2, v8, s[8:9]
	s_add_u32 s8, s8, s10
	s_addc_u32 s9, s9, s11
	v_mul_f32_e32 v9, v5, v7
	v_mul_f32_e32 v10, v5, v6
	v_fma_f32 v9, v4, v6, -v9
	v_fma_f32 v10, v4, v7, v10
	v_add_f32_e32 v6, v9, v72
	v_add_f32_e32 v7, v10, v73
	v_cvt_pk_bf16_f32 v8, v6, v7
	global_store_dword v2, v8, s[8:9]
	s_add_u32 s8, s8, s10
	s_addc_u32 s9, s9, s11
	v_mul_f32_e32 v9, v5, v7
	v_mul_f32_e32 v10, v5, v6
	v_fma_f32 v9, v4, v6, -v9
	v_fma_f32 v10, v4, v7, v10
	v_add_f32_e32 v6, v9, v74
	v_add_f32_e32 v7, v10, v75
	v_cvt_pk_bf16_f32 v8, v6, v7
	global_store_dword v2, v8, s[8:9]
	s_add_u32 s8, s8, s10
	s_addc_u32 s9, s9, s11
	v_mul_f32_e32 v9, v5, v7
	v_mul_f32_e32 v10, v5, v6
	v_fma_f32 v9, v4, v6, -v9
	v_fma_f32 v10, v4, v7, v10
	v_add_f32_e32 v6, v9, v76
	v_add_f32_e32 v7, v10, v77
	v_cvt_pk_bf16_f32 v8, v6, v7
	global_store_dword v2, v8, s[8:9]
	s_add_u32 s8, s8, s10
	s_addc_u32 s9, s9, s11
	v_mul_f32_e32 v9, v5, v7
	v_mul_f32_e32 v10, v5, v6
	v_fma_f32 v9, v4, v6, -v9
	v_fma_f32 v10, v4, v7, v10
	v_add_f32_e32 v6, v9, v78
	v_add_f32_e32 v7, v10, v79
	v_cvt_pk_bf16_f32 v8, v6, v7
	global_store_dword v2, v8, s[8:9]
	s_add_u32 s8, s8, s10
	s_addc_u32 s9, s9, s11
	v_mul_f32_e32 v9, v5, v7
	v_mul_f32_e32 v10, v5, v6
	v_fma_f32 v9, v4, v6, -v9
	v_fma_f32 v10, v4, v7, v10
	v_add_f32_e32 v6, v9, v80
	v_add_f32_e32 v7, v10, v81
	v_cvt_pk_bf16_f32 v8, v6, v7
	global_store_dword v2, v8, s[8:9]
	s_add_u32 s8, s8, s10
	s_addc_u32 s9, s9, s11
	v_mul_f32_e32 v9, v5, v7
	v_mul_f32_e32 v10, v5, v6
	v_fma_f32 v9, v4, v6, -v9
	v_fma_f32 v10, v4, v7, v10
	v_add_f32_e32 v6, v9, v82
	v_add_f32_e32 v7, v10, v83
	v_cvt_pk_bf16_f32 v8, v6, v7
	global_store_dword v2, v8, s[8:9]
	s_add_u32 s8, s8, s10
	s_addc_u32 s9, s9, s11
	v_mul_f32_e32 v9, v5, v7
	v_mul_f32_e32 v10, v5, v6
	v_fma_f32 v9, v4, v6, -v9
	v_fma_f32 v10, v4, v7, v10
	v_add_f32_e32 v6, v9, v84
	v_add_f32_e32 v7, v10, v85
	v_cvt_pk_bf16_f32 v8, v6, v7
	global_store_dword v2, v8, s[8:9]
	s_add_u32 s8, s8, s10
	s_addc_u32 s9, s9, s11
	v_mul_f32_e32 v9, v5, v7
	v_mul_f32_e32 v10, v5, v6
	v_fma_f32 v9, v4, v6, -v9
	v_fma_f32 v10, v4, v7, v10
	v_add_f32_e32 v6, v9, v86
	v_add_f32_e32 v7, v10, v87
	v_cvt_pk_bf16_f32 v8, v6, v7
	global_store_dword v2, v8, s[8:9]
	s_add_u32 s8, s8, s10
	s_addc_u32 s9, s9, s11
	v_mul_f32_e32 v9, v5, v7
	v_mul_f32_e32 v10, v5, v6
	v_fma_f32 v9, v4, v6, -v9
	v_fma_f32 v10, v4, v7, v10
	v_add_f32_e32 v6, v9, v88
	v_add_f32_e32 v7, v10, v89
	v_cvt_pk_bf16_f32 v8, v6, v7
	global_store_dword v2, v8, s[8:9]
	s_add_u32 s8, s8, s10
	s_addc_u32 s9, s9, s11
	v_mul_f32_e32 v9, v5, v7
	v_mul_f32_e32 v10, v5, v6
	v_fma_f32 v9, v4, v6, -v9
	v_fma_f32 v10, v4, v7, v10
	v_add_f32_e32 v6, v9, v90
	v_add_f32_e32 v7, v10, v91
	v_cvt_pk_bf16_f32 v8, v6, v7
	global_store_dword v2, v8, s[8:9]
	s_add_u32 s8, s8, s10
	s_addc_u32 s9, s9, s11
	v_mul_f32_e32 v9, v5, v7
	v_mul_f32_e32 v10, v5, v6
	v_fma_f32 v9, v4, v6, -v9
	v_fma_f32 v10, v4, v7, v10
	v_add_f32_e32 v6, v9, v92
	v_add_f32_e32 v7, v10, v93
	v_cvt_pk_bf16_f32 v8, v6, v7
	global_store_dword v2, v8, s[8:9]
	s_add_u32 s8, s8, s10
	s_addc_u32 s9, s9, s11
	v_mul_f32_e32 v9, v5, v7
	v_mul_f32_e32 v10, v5, v6
	v_fma_f32 v9, v4, v6, -v9
	v_fma_f32 v10, v4, v7, v10
	v_add_f32_e32 v6, v9, v94
	v_add_f32_e32 v7, v10, v95
	global_load_dwordx2 v[32:33], v1, s[0:1]
	s_add_u32 s0, s0, s10
	s_addc_u32 s1, s1, s11
	global_load_dwordx2 v[34:35], v1, s[0:1]
	s_add_u32 s0, s0, s10
	s_addc_u32 s1, s1, s11
	global_load_dwordx2 v[36:37], v1, s[0:1]
	s_add_u32 s0, s0, s10
	s_addc_u32 s1, s1, s11
	global_load_dwordx2 v[38:39], v1, s[0:1]
	s_add_u32 s0, s0, s10
	s_addc_u32 s1, s1, s11
	global_load_dwordx2 v[40:41], v1, s[0:1]
	s_add_u32 s0, s0, s10
	s_addc_u32 s1, s1, s11
	global_load_dwordx2 v[42:43], v1, s[0:1]
	s_add_u32 s0, s0, s10
	s_addc_u32 s1, s1, s11
	global_load_dwordx2 v[44:45], v1, s[0:1]
	s_add_u32 s0, s0, s10
	s_addc_u32 s1, s1, s11
	global_load_dwordx2 v[46:47], v1, s[0:1]
	s_add_u32 s0, s0, s10
	s_addc_u32 s1, s1, s11
	global_load_dwordx2 v[48:49], v1, s[0:1]
	s_add_u32 s0, s0, s10
	s_addc_u32 s1, s1, s11
	global_load_dwordx2 v[50:51], v1, s[0:1]
	s_add_u32 s0, s0, s10
	s_addc_u32 s1, s1, s11
	global_load_dwordx2 v[52:53], v1, s[0:1]
	s_add_u32 s0, s0, s10
	s_addc_u32 s1, s1, s11
	global_load_dwordx2 v[54:55], v1, s[0:1]
	s_add_u32 s0, s0, s10
	s_addc_u32 s1, s1, s11
	global_load_dwordx2 v[56:57], v1, s[0:1]
	s_add_u32 s0, s0, s10
	s_addc_u32 s1, s1, s11
	global_load_dwordx2 v[58:59], v1, s[0:1]
	s_add_u32 s0, s0, s10
	s_addc_u32 s1, s1, s11
	global_load_dwordx2 v[60:61], v1, s[0:1]
	s_add_u32 s0, s0, s10
	s_addc_u32 s1, s1, s11
	global_load_dwordx2 v[62:63], v1, s[0:1]
	s_add_u32 s0, s0, s10
	s_addc_u32 s1, s1, s11
	s_waitcnt vmcnt(32)
	v_cvt_pk_bf16_f32 v8, v6, v7
	global_store_dword v2, v8, s[8:9]
	s_add_u32 s8, s8, s10
	s_addc_u32 s9, s9, s11
	v_mul_f32_e32 v9, v5, v7
	v_mul_f32_e32 v10, v5, v6
	v_fma_f32 v9, v4, v6, -v9
	v_fma_f32 v10, v4, v7, v10
	v_add_f32_e32 v6, v9, v96
	v_add_f32_e32 v7, v10, v97
	v_cvt_pk_bf16_f32 v8, v6, v7
	global_store_dword v2, v8, s[8:9]
	s_add_u32 s8, s8, s10
	s_addc_u32 s9, s9, s11
	v_mul_f32_e32 v9, v5, v7
	v_mul_f32_e32 v10, v5, v6
	v_fma_f32 v9, v4, v6, -v9
	v_fma_f32 v10, v4, v7, v10
	v_add_f32_e32 v6, v9, v98
	v_add_f32_e32 v7, v10, v99
	v_cvt_pk_bf16_f32 v8, v6, v7
	global_store_dword v2, v8, s[8:9]
	s_add_u32 s8, s8, s10
	s_addc_u32 s9, s9, s11
	v_mul_f32_e32 v9, v5, v7
	v_mul_f32_e32 v10, v5, v6
	v_fma_f32 v9, v4, v6, -v9
	v_fma_f32 v10, v4, v7, v10
	v_add_f32_e32 v6, v9, v100
	v_add_f32_e32 v7, v10, v101
	v_cvt_pk_bf16_f32 v8, v6, v7
	global_store_dword v2, v8, s[8:9]
	s_add_u32 s8, s8, s10
	s_addc_u32 s9, s9, s11
	v_mul_f32_e32 v9, v5, v7
	v_mul_f32_e32 v10, v5, v6
	v_fma_f32 v9, v4, v6, -v9
	v_fma_f32 v10, v4, v7, v10
	v_add_f32_e32 v6, v9, v102
	v_add_f32_e32 v7, v10, v103
	v_cvt_pk_bf16_f32 v8, v6, v7
	global_store_dword v2, v8, s[8:9]
	s_add_u32 s8, s8, s10
	s_addc_u32 s9, s9, s11
	v_mul_f32_e32 v9, v5, v7
	v_mul_f32_e32 v10, v5, v6
	v_fma_f32 v9, v4, v6, -v9
	v_fma_f32 v10, v4, v7, v10
	v_add_f32_e32 v6, v9, v104
	v_add_f32_e32 v7, v10, v105
	v_cvt_pk_bf16_f32 v8, v6, v7
	global_store_dword v2, v8, s[8:9]
	s_add_u32 s8, s8, s10
	s_addc_u32 s9, s9, s11
	v_mul_f32_e32 v9, v5, v7
	v_mul_f32_e32 v10, v5, v6
	v_fma_f32 v9, v4, v6, -v9
	v_fma_f32 v10, v4, v7, v10
	v_add_f32_e32 v6, v9, v106
	v_add_f32_e32 v7, v10, v107
	v_cvt_pk_bf16_f32 v8, v6, v7
	global_store_dword v2, v8, s[8:9]
	s_add_u32 s8, s8, s10
	s_addc_u32 s9, s9, s11
	v_mul_f32_e32 v9, v5, v7
	v_mul_f32_e32 v10, v5, v6
	v_fma_f32 v9, v4, v6, -v9
	v_fma_f32 v10, v4, v7, v10
	v_add_f32_e32 v6, v9, v108
	v_add_f32_e32 v7, v10, v109
	v_cvt_pk_bf16_f32 v8, v6, v7
	global_store_dword v2, v8, s[8:9]
	s_add_u32 s8, s8, s10
	s_addc_u32 s9, s9, s11
	v_mul_f32_e32 v9, v5, v7
	v_mul_f32_e32 v10, v5, v6
	v_fma_f32 v9, v4, v6, -v9
	v_fma_f32 v10, v4, v7, v10
	v_add_f32_e32 v6, v9, v110
	v_add_f32_e32 v7, v10, v111
	v_cvt_pk_bf16_f32 v8, v6, v7
	global_store_dword v2, v8, s[8:9]
	s_add_u32 s8, s8, s10
	s_addc_u32 s9, s9, s11
	v_mul_f32_e32 v9, v5, v7
	v_mul_f32_e32 v10, v5, v6
	v_fma_f32 v9, v4, v6, -v9
	v_fma_f32 v10, v4, v7, v10
	v_add_f32_e32 v6, v9, v112
	v_add_f32_e32 v7, v10, v113
	v_cvt_pk_bf16_f32 v8, v6, v7
	global_store_dword v2, v8, s[8:9]
	s_add_u32 s8, s8, s10
	s_addc_u32 s9, s9, s11
	v_mul_f32_e32 v9, v5, v7
	v_mul_f32_e32 v10, v5, v6
	v_fma_f32 v9, v4, v6, -v9
	v_fma_f32 v10, v4, v7, v10
	v_add_f32_e32 v6, v9, v114
	v_add_f32_e32 v7, v10, v115
	v_cvt_pk_bf16_f32 v8, v6, v7
	global_store_dword v2, v8, s[8:9]
	s_add_u32 s8, s8, s10
	s_addc_u32 s9, s9, s11
	v_mul_f32_e32 v9, v5, v7
	v_mul_f32_e32 v10, v5, v6
	v_fma_f32 v9, v4, v6, -v9
	v_fma_f32 v10, v4, v7, v10
	v_add_f32_e32 v6, v9, v116
	v_add_f32_e32 v7, v10, v117
	v_cvt_pk_bf16_f32 v8, v6, v7
	global_store_dword v2, v8, s[8:9]
	s_add_u32 s8, s8, s10
	s_addc_u32 s9, s9, s11
	v_mul_f32_e32 v9, v5, v7
	v_mul_f32_e32 v10, v5, v6
	v_fma_f32 v9, v4, v6, -v9
	v_fma_f32 v10, v4, v7, v10
	v_add_f32_e32 v6, v9, v118
	v_add_f32_e32 v7, v10, v119
	v_cvt_pk_bf16_f32 v8, v6, v7
	global_store_dword v2, v8, s[8:9]
	s_add_u32 s8, s8, s10
	s_addc_u32 s9, s9, s11
	v_mul_f32_e32 v9, v5, v7
	v_mul_f32_e32 v10, v5, v6
	v_fma_f32 v9, v4, v6, -v9
	v_fma_f32 v10, v4, v7, v10
	v_add_f32_e32 v6, v9, v120
	v_add_f32_e32 v7, v10, v121
	v_cvt_pk_bf16_f32 v8, v6, v7
	global_store_dword v2, v8, s[8:9]
	s_add_u32 s8, s8, s10
	s_addc_u32 s9, s9, s11
	v_mul_f32_e32 v9, v5, v7
	v_mul_f32_e32 v10, v5, v6
	v_fma_f32 v9, v4, v6, -v9
	v_fma_f32 v10, v4, v7, v10
	v_add_f32_e32 v6, v9, v122
	v_add_f32_e32 v7, v10, v123
	v_cvt_pk_bf16_f32 v8, v6, v7
	global_store_dword v2, v8, s[8:9]
	s_add_u32 s8, s8, s10
	s_addc_u32 s9, s9, s11
	v_mul_f32_e32 v9, v5, v7
	v_mul_f32_e32 v10, v5, v6
	v_fma_f32 v9, v4, v6, -v9
	v_fma_f32 v10, v4, v7, v10
	v_add_f32_e32 v6, v9, v124
	v_add_f32_e32 v7, v10, v125
	v_cvt_pk_bf16_f32 v8, v6, v7
	global_store_dword v2, v8, s[8:9]
	s_add_u32 s8, s8, s10
	s_addc_u32 s9, s9, s11
	v_mul_f32_e32 v9, v5, v7
	v_mul_f32_e32 v10, v5, v6
	v_fma_f32 v9, v4, v6, -v9
	v_fma_f32 v10, v4, v7, v10
	v_add_f32_e32 v6, v9, v126
	v_add_f32_e32 v7, v10, v127
	global_load_dwordx2 v[64:65], v1, s[0:1]
	s_add_u32 s0, s0, s10
	s_addc_u32 s1, s1, s11
	global_load_dwordx2 v[66:67], v1, s[0:1]
	s_add_u32 s0, s0, s10
	s_addc_u32 s1, s1, s11
	global_load_dwordx2 v[68:69], v1, s[0:1]
	s_add_u32 s0, s0, s10
	s_addc_u32 s1, s1, s11
	global_load_dwordx2 v[70:71], v1, s[0:1]
	s_add_u32 s0, s0, s10
	s_addc_u32 s1, s1, s11
	global_load_dwordx2 v[72:73], v1, s[0:1]
	s_add_u32 s0, s0, s10
	s_addc_u32 s1, s1, s11
	global_load_dwordx2 v[74:75], v1, s[0:1]
	s_add_u32 s0, s0, s10
	s_addc_u32 s1, s1, s11
	global_load_dwordx2 v[76:77], v1, s[0:1]
	s_add_u32 s0, s0, s10
	s_addc_u32 s1, s1, s11
	global_load_dwordx2 v[78:79], v1, s[0:1]
	s_add_u32 s0, s0, s10
	s_addc_u32 s1, s1, s11
	global_load_dwordx2 v[80:81], v1, s[0:1]
	s_add_u32 s0, s0, s10
	s_addc_u32 s1, s1, s11
	global_load_dwordx2 v[82:83], v1, s[0:1]
	s_add_u32 s0, s0, s10
	s_addc_u32 s1, s1, s11
	global_load_dwordx2 v[84:85], v1, s[0:1]
	s_add_u32 s0, s0, s10
	s_addc_u32 s1, s1, s11
	global_load_dwordx2 v[86:87], v1, s[0:1]
	s_add_u32 s0, s0, s10
	s_addc_u32 s1, s1, s11
	global_load_dwordx2 v[88:89], v1, s[0:1]
	s_add_u32 s0, s0, s10
	s_addc_u32 s1, s1, s11
	global_load_dwordx2 v[90:91], v1, s[0:1]
	s_add_u32 s0, s0, s10
	s_addc_u32 s1, s1, s11
	global_load_dwordx2 v[92:93], v1, s[0:1]
	s_add_u32 s0, s0, s10
	s_addc_u32 s1, s1, s11
	global_load_dwordx2 v[94:95], v1, s[0:1]
	s_add_u32 s0, s0, s10
	s_addc_u32 s1, s1, s11
	s_waitcnt vmcnt(32)
	v_cvt_pk_bf16_f32 v8, v6, v7
	global_store_dword v2, v8, s[8:9]
	s_add_u32 s8, s8, s10
	s_addc_u32 s9, s9, s11
	v_mul_f32_e32 v9, v5, v7
	v_mul_f32_e32 v10, v5, v6
	v_fma_f32 v9, v4, v6, -v9
	v_fma_f32 v10, v4, v7, v10
	v_add_f32_e32 v6, v9, v32
	v_add_f32_e32 v7, v10, v33
	v_cvt_pk_bf16_f32 v8, v6, v7
	global_store_dword v2, v8, s[8:9]
	s_add_u32 s8, s8, s10
	s_addc_u32 s9, s9, s11
	v_mul_f32_e32 v9, v5, v7
	v_mul_f32_e32 v10, v5, v6
	v_fma_f32 v9, v4, v6, -v9
	v_fma_f32 v10, v4, v7, v10
	v_add_f32_e32 v6, v9, v34
	v_add_f32_e32 v7, v10, v35
	v_cvt_pk_bf16_f32 v8, v6, v7
	global_store_dword v2, v8, s[8:9]
	s_add_u32 s8, s8, s10
	s_addc_u32 s9, s9, s11
	v_mul_f32_e32 v9, v5, v7
	v_mul_f32_e32 v10, v5, v6
	v_fma_f32 v9, v4, v6, -v9
	v_fma_f32 v10, v4, v7, v10
	v_add_f32_e32 v6, v9, v36
	v_add_f32_e32 v7, v10, v37
	v_cvt_pk_bf16_f32 v8, v6, v7
	global_store_dword v2, v8, s[8:9]
	s_add_u32 s8, s8, s10
	s_addc_u32 s9, s9, s11
	v_mul_f32_e32 v9, v5, v7
	v_mul_f32_e32 v10, v5, v6
	v_fma_f32 v9, v4, v6, -v9
	v_fma_f32 v10, v4, v7, v10
	v_add_f32_e32 v6, v9, v38
	v_add_f32_e32 v7, v10, v39
	v_cvt_pk_bf16_f32 v8, v6, v7
	global_store_dword v2, v8, s[8:9]
	s_add_u32 s8, s8, s10
	s_addc_u32 s9, s9, s11
	v_mul_f32_e32 v9, v5, v7
	v_mul_f32_e32 v10, v5, v6
	v_fma_f32 v9, v4, v6, -v9
	v_fma_f32 v10, v4, v7, v10
	v_add_f32_e32 v6, v9, v40
	v_add_f32_e32 v7, v10, v41
	v_cvt_pk_bf16_f32 v8, v6, v7
	global_store_dword v2, v8, s[8:9]
	s_add_u32 s8, s8, s10
	s_addc_u32 s9, s9, s11
	v_mul_f32_e32 v9, v5, v7
	v_mul_f32_e32 v10, v5, v6
	v_fma_f32 v9, v4, v6, -v9
	v_fma_f32 v10, v4, v7, v10
	v_add_f32_e32 v6, v9, v42
	v_add_f32_e32 v7, v10, v43
	v_cvt_pk_bf16_f32 v8, v6, v7
	global_store_dword v2, v8, s[8:9]
	s_add_u32 s8, s8, s10
	s_addc_u32 s9, s9, s11
	v_mul_f32_e32 v9, v5, v7
	v_mul_f32_e32 v10, v5, v6
	v_fma_f32 v9, v4, v6, -v9
	v_fma_f32 v10, v4, v7, v10
	v_add_f32_e32 v6, v9, v44
	v_add_f32_e32 v7, v10, v45
	v_cvt_pk_bf16_f32 v8, v6, v7
	global_store_dword v2, v8, s[8:9]
	s_add_u32 s8, s8, s10
	s_addc_u32 s9, s9, s11
	v_mul_f32_e32 v9, v5, v7
	v_mul_f32_e32 v10, v5, v6
	v_fma_f32 v9, v4, v6, -v9
	v_fma_f32 v10, v4, v7, v10
	v_add_f32_e32 v6, v9, v46
	v_add_f32_e32 v7, v10, v47
	v_cvt_pk_bf16_f32 v8, v6, v7
	global_store_dword v2, v8, s[8:9]
	s_add_u32 s8, s8, s10
	s_addc_u32 s9, s9, s11
	v_mul_f32_e32 v9, v5, v7
	v_mul_f32_e32 v10, v5, v6
	v_fma_f32 v9, v4, v6, -v9
	v_fma_f32 v10, v4, v7, v10
	v_add_f32_e32 v6, v9, v48
	v_add_f32_e32 v7, v10, v49
	v_cvt_pk_bf16_f32 v8, v6, v7
	global_store_dword v2, v8, s[8:9]
	s_add_u32 s8, s8, s10
	s_addc_u32 s9, s9, s11
	v_mul_f32_e32 v9, v5, v7
	v_mul_f32_e32 v10, v5, v6
	v_fma_f32 v9, v4, v6, -v9
	v_fma_f32 v10, v4, v7, v10
	v_add_f32_e32 v6, v9, v50
	v_add_f32_e32 v7, v10, v51
	v_cvt_pk_bf16_f32 v8, v6, v7
	global_store_dword v2, v8, s[8:9]
	s_add_u32 s8, s8, s10
	s_addc_u32 s9, s9, s11
	v_mul_f32_e32 v9, v5, v7
	v_mul_f32_e32 v10, v5, v6
	v_fma_f32 v9, v4, v6, -v9
	v_fma_f32 v10, v4, v7, v10
	v_add_f32_e32 v6, v9, v52
	v_add_f32_e32 v7, v10, v53
	v_cvt_pk_bf16_f32 v8, v6, v7
	global_store_dword v2, v8, s[8:9]
	s_add_u32 s8, s8, s10
	s_addc_u32 s9, s9, s11
	v_mul_f32_e32 v9, v5, v7
	v_mul_f32_e32 v10, v5, v6
	v_fma_f32 v9, v4, v6, -v9
	v_fma_f32 v10, v4, v7, v10
	v_add_f32_e32 v6, v9, v54
	v_add_f32_e32 v7, v10, v55
	v_cvt_pk_bf16_f32 v8, v6, v7
	global_store_dword v2, v8, s[8:9]
	s_add_u32 s8, s8, s10
	s_addc_u32 s9, s9, s11
	v_mul_f32_e32 v9, v5, v7
	v_mul_f32_e32 v10, v5, v6
	v_fma_f32 v9, v4, v6, -v9
	v_fma_f32 v10, v4, v7, v10
	v_add_f32_e32 v6, v9, v56
	v_add_f32_e32 v7, v10, v57
	v_cvt_pk_bf16_f32 v8, v6, v7
	global_store_dword v2, v8, s[8:9]
	s_add_u32 s8, s8, s10
	s_addc_u32 s9, s9, s11
	v_mul_f32_e32 v9, v5, v7
	v_mul_f32_e32 v10, v5, v6
	v_fma_f32 v9, v4, v6, -v9
	v_fma_f32 v10, v4, v7, v10
	v_add_f32_e32 v6, v9, v58
	v_add_f32_e32 v7, v10, v59
	v_cvt_pk_bf16_f32 v8, v6, v7
	global_store_dword v2, v8, s[8:9]
	s_add_u32 s8, s8, s10
	s_addc_u32 s9, s9, s11
	v_mul_f32_e32 v9, v5, v7
	v_mul_f32_e32 v10, v5, v6
	v_fma_f32 v9, v4, v6, -v9
	v_fma_f32 v10, v4, v7, v10
	v_add_f32_e32 v6, v9, v60
	v_add_f32_e32 v7, v10, v61
	v_cvt_pk_bf16_f32 v8, v6, v7
	global_store_dword v2, v8, s[8:9]
	s_add_u32 s8, s8, s10
	s_addc_u32 s9, s9, s11
	v_mul_f32_e32 v9, v5, v7
	v_mul_f32_e32 v10, v5, v6
	v_fma_f32 v9, v4, v6, -v9
	v_fma_f32 v10, v4, v7, v10
	v_add_f32_e32 v6, v9, v62
	v_add_f32_e32 v7, v10, v63
	s_waitcnt vmcnt(16)
	v_cvt_pk_bf16_f32 v8, v6, v7
	global_store_dword v2, v8, s[8:9]
	s_add_u32 s8, s8, s10
	s_addc_u32 s9, s9, s11
	v_mul_f32_e32 v9, v5, v7
	v_mul_f32_e32 v10, v5, v6
	v_fma_f32 v9, v4, v6, -v9
	v_fma_f32 v10, v4, v7, v10
	v_add_f32_e32 v6, v9, v64
	v_add_f32_e32 v7, v10, v65
	v_cvt_pk_bf16_f32 v8, v6, v7
	global_store_dword v2, v8, s[8:9]
	s_add_u32 s8, s8, s10
	s_addc_u32 s9, s9, s11
	v_mul_f32_e32 v9, v5, v7
	v_mul_f32_e32 v10, v5, v6
	v_fma_f32 v9, v4, v6, -v9
	v_fma_f32 v10, v4, v7, v10
	v_add_f32_e32 v6, v9, v66
	v_add_f32_e32 v7, v10, v67
	v_cvt_pk_bf16_f32 v8, v6, v7
	global_store_dword v2, v8, s[8:9]
	s_add_u32 s8, s8, s10
	s_addc_u32 s9, s9, s11
	v_mul_f32_e32 v9, v5, v7
	v_mul_f32_e32 v10, v5, v6
	v_fma_f32 v9, v4, v6, -v9
	v_fma_f32 v10, v4, v7, v10
	v_add_f32_e32 v6, v9, v68
	v_add_f32_e32 v7, v10, v69
	v_cvt_pk_bf16_f32 v8, v6, v7
	global_store_dword v2, v8, s[8:9]
	s_add_u32 s8, s8, s10
	s_addc_u32 s9, s9, s11
	v_mul_f32_e32 v9, v5, v7
	v_mul_f32_e32 v10, v5, v6
	v_fma_f32 v9, v4, v6, -v9
	v_fma_f32 v10, v4, v7, v10
	v_add_f32_e32 v6, v9, v70
	v_add_f32_e32 v7, v10, v71
	v_cvt_pk_bf16_f32 v8, v6, v7
	global_store_dword v2, v8, s[8:9]
	s_add_u32 s8, s8, s10
	s_addc_u32 s9, s9, s11
	v_mul_f32_e32 v9, v5, v7
	v_mul_f32_e32 v10, v5, v6
	v_fma_f32 v9, v4, v6, -v9
	v_fma_f32 v10, v4, v7, v10
	v_add_f32_e32 v6, v9, v72
	v_add_f32_e32 v7, v10, v73
	v_cvt_pk_bf16_f32 v8, v6, v7
	global_store_dword v2, v8, s[8:9]
	s_add_u32 s8, s8, s10
	s_addc_u32 s9, s9, s11
	v_mul_f32_e32 v9, v5, v7
	v_mul_f32_e32 v10, v5, v6
	v_fma_f32 v9, v4, v6, -v9
	v_fma_f32 v10, v4, v7, v10
	v_add_f32_e32 v6, v9, v74
	v_add_f32_e32 v7, v10, v75
	v_cvt_pk_bf16_f32 v8, v6, v7
	global_store_dword v2, v8, s[8:9]
	s_add_u32 s8, s8, s10
	s_addc_u32 s9, s9, s11
	v_mul_f32_e32 v9, v5, v7
	v_mul_f32_e32 v10, v5, v6
	v_fma_f32 v9, v4, v6, -v9
	v_fma_f32 v10, v4, v7, v10
	v_add_f32_e32 v6, v9, v76
	v_add_f32_e32 v7, v10, v77
	v_cvt_pk_bf16_f32 v8, v6, v7
	global_store_dword v2, v8, s[8:9]
	s_add_u32 s8, s8, s10
	s_addc_u32 s9, s9, s11
	v_mul_f32_e32 v9, v5, v7
	v_mul_f32_e32 v10, v5, v6
	v_fma_f32 v9, v4, v6, -v9
	v_fma_f32 v10, v4, v7, v10
	v_add_f32_e32 v6, v9, v78
	v_add_f32_e32 v7, v10, v79
	v_cvt_pk_bf16_f32 v8, v6, v7
	global_store_dword v2, v8, s[8:9]
	s_add_u32 s8, s8, s10
	s_addc_u32 s9, s9, s11
	v_mul_f32_e32 v9, v5, v7
	v_mul_f32_e32 v10, v5, v6
	v_fma_f32 v9, v4, v6, -v9
	v_fma_f32 v10, v4, v7, v10
	v_add_f32_e32 v6, v9, v80
	v_add_f32_e32 v7, v10, v81
	v_cvt_pk_bf16_f32 v8, v6, v7
	global_store_dword v2, v8, s[8:9]
	s_add_u32 s8, s8, s10
	s_addc_u32 s9, s9, s11
	v_mul_f32_e32 v9, v5, v7
	v_mul_f32_e32 v10, v5, v6
	v_fma_f32 v9, v4, v6, -v9
	v_fma_f32 v10, v4, v7, v10
	v_add_f32_e32 v6, v9, v82
	v_add_f32_e32 v7, v10, v83
	v_cvt_pk_bf16_f32 v8, v6, v7
	global_store_dword v2, v8, s[8:9]
	s_add_u32 s8, s8, s10
	s_addc_u32 s9, s9, s11
	v_mul_f32_e32 v9, v5, v7
	v_mul_f32_e32 v10, v5, v6
	v_fma_f32 v9, v4, v6, -v9
	v_fma_f32 v10, v4, v7, v10
	v_add_f32_e32 v6, v9, v84
	v_add_f32_e32 v7, v10, v85
	v_cvt_pk_bf16_f32 v8, v6, v7
	global_store_dword v2, v8, s[8:9]
	s_add_u32 s8, s8, s10
	s_addc_u32 s9, s9, s11
	v_mul_f32_e32 v9, v5, v7
	v_mul_f32_e32 v10, v5, v6
	v_fma_f32 v9, v4, v6, -v9
	v_fma_f32 v10, v4, v7, v10
	v_add_f32_e32 v6, v9, v86
	v_add_f32_e32 v7, v10, v87
	v_cvt_pk_bf16_f32 v8, v6, v7
	global_store_dword v2, v8, s[8:9]
	s_add_u32 s8, s8, s10
	s_addc_u32 s9, s9, s11
	v_mul_f32_e32 v9, v5, v7
	v_mul_f32_e32 v10, v5, v6
	v_fma_f32 v9, v4, v6, -v9
	v_fma_f32 v10, v4, v7, v10
	v_add_f32_e32 v6, v9, v88
	v_add_f32_e32 v7, v10, v89
	v_cvt_pk_bf16_f32 v8, v6, v7
	global_store_dword v2, v8, s[8:9]
	s_add_u32 s8, s8, s10
	s_addc_u32 s9, s9, s11
	v_mul_f32_e32 v9, v5, v7
	v_mul_f32_e32 v10, v5, v6
	v_fma_f32 v9, v4, v6, -v9
	v_fma_f32 v10, v4, v7, v10
	v_add_f32_e32 v6, v9, v90
	v_add_f32_e32 v7, v10, v91
	v_cvt_pk_bf16_f32 v8, v6, v7
	global_store_dword v2, v8, s[8:9]
	s_add_u32 s8, s8, s10
	s_addc_u32 s9, s9, s11
	v_mul_f32_e32 v9, v5, v7
	v_mul_f32_e32 v10, v5, v6
	v_fma_f32 v9, v4, v6, -v9
	v_fma_f32 v10, v4, v7, v10
	v_add_f32_e32 v6, v9, v92
	v_add_f32_e32 v7, v10, v93
	v_cvt_pk_bf16_f32 v8, v6, v7
	global_store_dword v2, v8, s[8:9]
	s_add_u32 s8, s8, s10
	s_addc_u32 s9, s9, s11
	v_mul_f32_e32 v9, v5, v7
	v_mul_f32_e32 v10, v5, v6
	v_fma_f32 v9, v4, v6, -v9
	v_fma_f32 v10, v4, v7, v10
	v_add_f32_e32 v6, v9, v94
	v_add_f32_e32 v7, v10, v95
	s_branch .Lscan_end
.Lscan_ctx:
	s_add_i32 s16, s21, 0
	s_lshl_b32 s19, s16, 4
	s_mul_i32 s17, s20, 0x300
	s_add_i32 s17, s17, s19
	s_mul_i32 s18, s25, 15
	s_add_i32 s17, s17, s18
	s_lshl_b32 s17, s17, 10
	s_lshl_b32 s18, s25, 9
	s_add_u32 s0, s54, 0x4200000
	s_addc_u32 s1, s55, 0
	s_add_u32 s0, s0, s17
	s_addc_u32 s1, s1, 0
	s_add_u32 s0, s0, s18
	s_addc_u32 s1, s1, 0
	s_lshl_b32 s18, s25, 8
	s_add_u32 s8, s54, 0xa200000
	s_addc_u32 s9, s55, 0
	s_add_u32 s8, s8, s17
	s_addc_u32 s9, s9, 0
	s_add_u32 s8, s8, s18
	s_addc_u32 s9, s9, 0
	s_add_u32 s8, s8, 0x200
	s_addc_u32 s9, s9, 0
	global_load_dwordx2 v[32:33], v1, s[0:1]
	s_add_u32 s0, s0, s10
	s_addc_u32 s1, s1, s11
	global_load_dwordx2 v[34:35], v1, s[0:1]
	s_add_u32 s0, s0, s10
	s_addc_u32 s1, s1, s11
	global_load_dwordx2 v[36:37], v1, s[0:1]
	s_add_u32 s0, s0, s10
	s_addc_u32 s1, s1, s11
	global_load_dwordx2 v[38:39], v1, s[0:1]
	s_add_u32 s0, s0, s10
	s_addc_u32 s1, s1, s11
	global_load_dwordx2 v[40:41], v1, s[0:1]
	s_add_u32 s0, s0, s10
	s_addc_u32 s1, s1, s11
	global_load_dwordx2 v[42:43], v1, s[0:1]
	s_add_u32 s0, s0, s10
	s_addc_u32 s1, s1, s11
	global_load_dwordx2 v[44:45], v1, s[0:1]
	s_add_u32 s0, s0, s10
	s_addc_u32 s1, s1, s11
	global_load_dwordx2 v[46:47], v1, s[0:1]
	s_add_u32 s0, s0, s10
	s_addc_u32 s1, s1, s11
	global_load_dwordx2 v[48:49], v1, s[0:1]
	s_add_u32 s0, s0, s10
	s_addc_u32 s1, s1, s11
	global_load_dwordx2 v[50:51], v1, s[0:1]
	s_add_u32 s0, s0, s10
	s_addc_u32 s1, s1, s11
	global_load_dwordx2 v[52:53], v1, s[0:1]
	s_add_u32 s0, s0, s10
	s_addc_u32 s1, s1, s11
	global_load_dwordx2 v[54:55], v1, s[0:1]
	s_add_u32 s0, s0, s10
	s_addc_u32 s1, s1, s11
	global_load_dwordx2 v[56:57], v1, s[0:1]
	s_add_u32 s0, s0, s10
	s_addc_u32 s1, s1, s11
	global_load_dwordx2 v[58:59], v1, s[0:1]
	s_add_u32 s0, s0, s10
	s_addc_u32 s1, s1, s11
	global_load_dwordx2 v[60:61], v1, s[0:1]
	s_add_u32 s0, s0, s10
	s_addc_u32 s1, s1, s11
	global_load_dwordx2 v[62:63], v1, s[0:1]
	s_add_u32 s0, s0, s10
	s_addc_u32 s1, s1, s11
	s_add_i32 s16, s21, 4
	s_lshl_b32 s19, s16, 4
	s_mul_i32 s17, s20, 0x300
	s_add_i32 s17, s17, s19
	s_mul_i32 s18, s25, 15
	s_add_i32 s17, s17, s18
	s_lshl_b32 s17, s17, 10
	s_lshl_b32 s18, s25, 9
	s_add_u32 s0, s54, 0x4200000
	s_addc_u32 s1, s55, 0
	s_add_u32 s0, s0, s17
	s_addc_u32 s1, s1, 0
	s_add_u32 s0, s0, s18
	s_addc_u32 s1, s1, 0
	s_lshl_b32 s18, s25, 8
	s_add_u32 s8, s54, 0xa200000
	s_addc_u32 s9, s55, 0
	s_add_u32 s8, s8, s17
	s_addc_u32 s9, s9, 0
	s_add_u32 s8, s8, s18
	s_addc_u32 s9, s9, 0
	s_add_u32 s8, s8, 0x200
	s_addc_u32 s9, s9, 0
	global_load_dwordx2 v[64:65], v1, s[0:1]
	s_add_u32 s0, s0, s10
	s_addc_u32 s1, s1, s11
	global_load_dwordx2 v[66:67], v1, s[0:1]
	s_add_u32 s0, s0, s10
	s_addc_u32 s1, s1, s11
	global_load_dwordx2 v[68:69], v1, s[0:1]
	s_add_u32 s0, s0, s10
	s_addc_u32 s1, s1, s11
	global_load_dwordx2 v[70:71], v1, s[0:1]
	s_add_u32 s0, s0, s10
	s_addc_u32 s1, s1, s11
	global_load_dwordx2 v[72:73], v1, s[0:1]
	s_add_u32 s0, s0, s10
	s_addc_u32 s1, s1, s11
	global_load_dwordx2 v[74:75], v1, s[0:1]
	s_add_u32 s0, s0, s10
	s_addc_u32 s1, s1, s11
	global_load_dwordx2 v[76:77], v1, s[0:1]
	s_add_u32 s0, s0, s10
	s_addc_u32 s1, s1, s11
	global_load_dwordx2 v[78:79], v1, s[0:1]
	s_add_u32 s0, s0, s10
	s_addc_u32 s1, s1, s11
	global_load_dwordx2 v[80:81], v1, s[0:1]
	s_add_u32 s0, s0, s10
	s_addc_u32 s1, s1, s11
	global_load_dwordx2 v[82:83], v1, s[0:1]
	s_add_u32 s0, s0, s10
	s_addc_u32 s1, s1, s11
	global_load_dwordx2 v[84:85], v1, s[0:1]
	s_add_u32 s0, s0, s10
	s_addc_u32 s1, s1, s11
	global_load_dwordx2 v[86:87], v1, s[0:1]
	s_add_u32 s0, s0, s10
	s_addc_u32 s1, s1, s11
	global_load_dwordx2 v[88:89], v1, s[0:1]
	s_add_u32 s0, s0, s10
	s_addc_u32 s1, s1, s11
	global_load_dwordx2 v[90:91], v1, s[0:1]
	s_add_u32 s0, s0, s10
	s_addc_u32 s1, s1, s11
	global_load_dwordx2 v[92:93], v1, s[0:1]
	s_add_u32 s0, s0, s10
	s_addc_u32 s1, s1, s11
	global_load_dwordx2 v[94:95], v1, s[0:1]
	s_add_u32 s0, s0, s10
	s_addc_u32 s1, s1, s11
	s_add_i32 s16, s21, 0
	s_lshl_b32 s19, s16, 4
	s_mul_i32 s17, s20, 0x300
	s_add_i32 s17, s17, s19
	s_mul_i32 s18, s25, 15
	s_add_i32 s17, s17, s18
	s_lshl_b32 s17, s17, 10
	s_lshl_b32 s18, s25, 8
	s_add_u32 s8, s54, 0xa200000
	s_addc_u32 s9, s55, 0
	s_add_u32 s8, s8, s17
	s_addc_u32 s9, s9, 0
	s_add_u32 s8, s8, s18
	s_addc_u32 s9, s9, 0
	s_add_u32 s8, s8, 0x200
	s_addc_u32 s9, s9, 0
	v_mov_b32_e32 v6, 0
	v_mov_b32_e32 v7, 0
	s_waitcnt vmcnt(16)
	v_cvt_pk_bf16_f32 v8, v6, v7
	global_store_dword v2, v8, s[8:9]
	s_add_u32 s8, s8, s10
	s_addc_u32 s9, s9, s11
	v_mul_f32_e32 v9, v5, v7
	v_mul_f32_e32 v10, v5, v6
	v_fma_f32 v9, v4, v6, -v9
	v_fma_f32 v10, v4, v7, v10
	v_add_f32_e32 v6, v9, v32
	v_add_f32_e32 v7, v10, v33
	v_cvt_pk_bf16_f32 v8, v6, v7
	global_store_dword v2, v8, s[8:9]
	s_add_u32 s8, s8, s10
	s_addc_u32 s9, s9, s11
	v_mul_f32_e32 v9, v5, v7
	v_mul_f32_e32 v10, v5, v6
	v_fma_f32 v9, v4, v6, -v9
	v_fma_f32 v10, v4, v7, v10
	v_add_f32_e32 v6, v9, v34
	v_add_f32_e32 v7, v10, v35
	v_cvt_pk_bf16_f32 v8, v6, v7
	global_store_dword v2, v8, s[8:9]
	s_add_u32 s8, s8, s10
	s_addc_u32 s9, s9, s11
	v_mul_f32_e32 v9, v5, v7
	v_mul_f32_e32 v10, v5, v6
	v_fma_f32 v9, v4, v6, -v9
	v_fma_f32 v10, v4, v7, v10
	v_add_f32_e32 v6, v9, v36
	v_add_f32_e32 v7, v10, v37
	v_cvt_pk_bf16_f32 v8, v6, v7
	global_store_dword v2, v8, s[8:9]
	s_add_u32 s8, s8, s10
	s_addc_u32 s9, s9, s11
	v_mul_f32_e32 v9, v5, v7
	v_mul_f32_e32 v10, v5, v6
	v_fma_f32 v9, v4, v6, -v9
	v_fma_f32 v10, v4, v7, v10
	v_add_f32_e32 v6, v9, v38
	v_add_f32_e32 v7, v10, v39
	v_cvt_pk_bf16_f32 v8, v6, v7
	global_store_dword v2, v8, s[8:9]
	s_add_u32 s8, s8, s10
	s_addc_u32 s9, s9, s11
	v_mul_f32_e32 v9, v5, v7
	v_mul_f32_e32 v10, v5, v6
	v_fma_f32 v9, v4, v6, -v9
	v_fma_f32 v10, v4, v7, v10
	v_add_f32_e32 v6, v9, v40
	v_add_f32_e32 v7, v10, v41
	v_cvt_pk_bf16_f32 v8, v6, v7
	global_store_dword v2, v8, s[8:9]
	s_add_u32 s8, s8, s10
	s_addc_u32 s9, s9, s11
	v_mul_f32_e32 v9, v5, v7
	v_mul_f32_e32 v10, v5, v6
	v_fma_f32 v9, v4, v6, -v9
	v_fma_f32 v10, v4, v7, v10
	v_add_f32_e32 v6, v9, v42
	v_add_f32_e32 v7, v10, v43
	v_cvt_pk_bf16_f32 v8, v6, v7
	global_store_dword v2, v8, s[8:9]
	s_add_u32 s8, s8, s10
	s_addc_u32 s9, s9, s11
	v_mul_f32_e32 v9, v5, v7
	v_mul_f32_e32 v10, v5, v6
	v_fma_f32 v9, v4, v6, -v9
	v_fma_f32 v10, v4, v7, v10
	v_add_f32_e32 v6, v9, v44
	v_add_f32_e32 v7, v10, v45
	v_cvt_pk_bf16_f32 v8, v6, v7
	global_store_dword v2, v8, s[8:9]
	s_add_u32 s8, s8, s10
	s_addc_u32 s9, s9, s11
	v_mul_f32_e32 v9, v5, v7
	v_mul_f32_e32 v10, v5, v6
	v_fma_f32 v9, v4, v6, -v9
	v_fma_f32 v10, v4, v7, v10
	v_add_f32_e32 v6, v9, v46
	v_add_f32_e32 v7, v10, v47
	v_cvt_pk_bf16_f32 v8, v6, v7
	global_store_dword v2, v8, s[8:9]
	s_add_u32 s8, s8, s10
	s_addc_u32 s9, s9, s11
	v_mul_f32_e32 v9, v5, v7
	v_mul_f32_e32 v10, v5, v6
	v_fma_f32 v9, v4, v6, -v9
	v_fma_f32 v10, v4, v7, v10
	v_add_f32_e32 v6, v9, v48
	v_add_f32_e32 v7, v10, v49
	v_cvt_pk_bf16_f32 v8, v6, v7
	global_store_dword v2, v8, s[8:9]
	s_add_u32 s8, s8, s10
	s_addc_u32 s9, s9, s11
	v_mul_f32_e32 v9, v5, v7
	v_mul_f32_e32 v10, v5, v6
	v_fma_f32 v9, v4, v6, -v9
	v_fma_f32 v10, v4, v7, v10
	v_add_f32_e32 v6, v9, v50
	v_add_f32_e32 v7, v10, v51
	v_cvt_pk_bf16_f32 v8, v6, v7
	global_store_dword v2, v8, s[8:9]
	s_add_u32 s8, s8, s10
	s_addc_u32 s9, s9, s11
	v_mul_f32_e32 v9, v5, v7
	v_mul_f32_e32 v10, v5, v6
	v_fma_f32 v9, v4, v6, -v9
	v_fma_f32 v10, v4, v7, v10
	v_add_f32_e32 v6, v9, v52
	v_add_f32_e32 v7, v10, v53
	v_cvt_pk_bf16_f32 v8, v6, v7
	global_store_dword v2, v8, s[8:9]
	s_add_u32 s8, s8, s10
	s_addc_u32 s9, s9, s11
	v_mul_f32_e32 v9, v5, v7
	v_mul_f32_e32 v10, v5, v6
	v_fma_f32 v9, v4, v6, -v9
	v_fma_f32 v10, v4, v7, v10
	v_add_f32_e32 v6, v9, v54
	v_add_f32_e32 v7, v10, v55
	v_cvt_pk_bf16_f32 v8, v6, v7
	global_store_dword v2, v8, s[8:9]
	s_add_u32 s8, s8, s10
	s_addc_u32 s9, s9, s11
	v_mul_f32_e32 v9, v5, v7
	v_mul_f32_e32 v10, v5, v6
	v_fma_f32 v9, v4, v6, -v9
	v_fma_f32 v10, v4, v7, v10
	v_add_f32_e32 v6, v9, v56
	v_add_f32_e32 v7, v10, v57
	v_cvt_pk_bf16_f32 v8, v6, v7
	global_store_dword v2, v8, s[8:9]
	s_add_u32 s8, s8, s10
	s_addc_u32 s9, s9, s11
	v_mul_f32_e32 v9, v5, v7
	v_mul_f32_e32 v10, v5, v6
	v_fma_f32 v9, v4, v6, -v9
	v_fma_f32 v10, v4, v7, v10
	v_add_f32_e32 v6, v9, v58
	v_add_f32_e32 v7, v10, v59
	v_cvt_pk_bf16_f32 v8, v6, v7
	global_store_dword v2, v8, s[8:9]
	s_add_u32 s8, s8, s10
	s_addc_u32 s9, s9, s11
	v_mul_f32_e32 v9, v5, v7
	v_mul_f32_e32 v10, v5, v6
	v_fma_f32 v9, v4, v6, -v9
	v_fma_f32 v10, v4, v7, v10
	v_add_f32_e32 v6, v9, v60
	v_add_f32_e32 v7, v10, v61
	v_cvt_pk_bf16_f32 v8, v6, v7
	global_store_dword v2, v8, s[8:9]
	s_add_u32 s8, s8, s10
	s_addc_u32 s9, s9, s11
	v_mul_f32_e32 v9, v5, v7
	v_mul_f32_e32 v10, v5, v6
	v_fma_f32 v9, v4, v6, -v9
	v_fma_f32 v10, v4, v7, v10
	v_add_f32_e32 v6, v9, v62
	v_add_f32_e32 v7, v10, v63
	s_lshl_b32 s17, s16, 1
	s_add_i32 s17, s17, s25
	s_lshl_b32 s17, s17, 5
	s_add_i32 s17, s17, s20
	s_lshl_b32 s17, s17, 8
	s_add_u32 s62, s52, s17
	s_addc_u32 s63, s53, 0
	s_add_u32 s62, s62, 0x4000000
	s_addc_u32 s63, s63, 0
	global_store_dword v2, v6, s[62:63]
	s_add_u32 s62, s62, 0x40000
	s_addc_u32 s63, s63, 0
	global_store_dword v2, v7, s[62:63]
	s_add_i32 s16, s21, 8
	s_lshl_b32 s19, s16, 4
	s_mul_i32 s17, s20, 0x300
	s_add_i32 s17, s17, s19
	s_mul_i32 s18, s25, 15
	s_add_i32 s17, s17, s18
	s_lshl_b32 s17, s17, 10
	s_lshl_b32 s18, s25, 9
	s_add_u32 s0, s54, 0x4200000
	s_addc_u32 s1, s55, 0
	s_add_u32 s0, s0, s17
	s_addc_u32 s1, s1, 0
	s_add_u32 s0, s0, s18
	s_addc_u32 s1, s1, 0
	s_lshl_b32 s18, s25, 8
	s_add_u32 s8, s54, 0xa200000
	s_addc_u32 s9, s55, 0
	s_add_u32 s8, s8, s17
	s_addc_u32 s9, s9, 0
	s_add_u32 s8, s8, s18
	s_addc_u32 s9, s9, 0
	s_add_u32 s8, s8, 0x200
	s_addc_u32 s9, s9, 0
	global_load_dwordx2 v[96:97], v1, s[0:1]
	s_add_u32 s0, s0, s10
	s_addc_u32 s1, s1, s11
	global_load_dwordx2 v[98:99], v1, s[0:1]
	s_add_u32 s0, s0, s10
	s_addc_u32 s1, s1, s11
	global_load_dwordx2 v[100:101], v1, s[0:1]
	s_add_u32 s0, s0, s10
	s_addc_u32 s1, s1, s11
	global_load_dwordx2 v[102:103], v1, s[0:1]
	s_add_u32 s0, s0, s10
	s_addc_u32 s1, s1, s11
	global_load_dwordx2 v[104:105], v1, s[0:1]
	s_add_u32 s0, s0, s10
	s_addc_u32 s1, s1, s11
	global_load_dwordx2 v[106:107], v1, s[0:1]
	s_add_u32 s0, s0, s10
	s_addc_u32 s1, s1, s11
	global_load_dwordx2 v[108:109], v1, s[0:1]
	s_add_u32 s0, s0, s10
	s_addc_u32 s1, s1, s11
	global_load_dwordx2 v[110:111], v1, s[0:1]
	s_add_u32 s0, s0, s10
	s_addc_u32 s1, s1, s11
	global_load_dwordx2 v[112:113], v1, s[0:1]
	s_add_u32 s0, s0, s10
	s_addc_u32 s1, s1, s11
	global_load_dwordx2 v[114:115], v1, s[0:1]
	s_add_u32 s0, s0, s10
	s_addc_u32 s1, s1, s11
	global_load_dwordx2 v[116:117], v1, s[0:1]
	s_add_u32 s0, s0, s10
	s_addc_u32 s1, s1, s11
	global_load_dwordx2 v[118:119], v1, s[0:1]
	s_add_u32 s0, s0, s10
	s_addc_u32 s1, s1, s11
	global_load_dwordx2 v[120:121], v1, s[0:1]
	s_add_u32 s0, s0, s10
	s_addc_u32 s1, s1, s11
	global_load_dwordx2 v[122:123], v1, s[0:1]
	s_add_u32 s0, s0, s10
	s_addc_u32 s1, s1, s11
	global_load_dwordx2 v[124:125], v1, s[0:1]
	s_add_u32 s0, s0, s10
	s_addc_u32 s1, s1, s11
	global_load_dwordx2 v[126:127], v1, s[0:1]
	s_add_u32 s0, s0, s10
	s_addc_u32 s1, s1, s11
	s_add_i32 s16, s21, 4
	s_lshl_b32 s19, s16, 4
	s_mul_i32 s17, s20, 0x300
	s_add_i32 s17, s17, s19
	s_mul_i32 s18, s25, 15
	s_add_i32 s17, s17, s18
	s_lshl_b32 s17, s17, 10
	s_lshl_b32 s18, s25, 8
	s_add_u32 s8, s54, 0xa200000
	s_addc_u32 s9, s55, 0
	s_add_u32 s8, s8, s17
	s_addc_u32 s9, s9, 0
	s_add_u32 s8, s8, s18
	s_addc_u32 s9, s9, 0
	s_add_u32 s8, s8, 0x200
	s_addc_u32 s9, s9, 0
	v_mov_b32_e32 v6, 0
	v_mov_b32_e32 v7, 0
	s_waitcnt vmcnt(34)
	v_cvt_pk_bf16_f32 v8, v6, v7
	global_store_dword v2, v8, s[8:9]
	s_add_u32 s8, s8, s10
	s_addc_u32 s9, s9, s11
	v_mul_f32_e32 v9, v5, v7
	v_mul_f32_e32 v10, v5, v6
	v_fma_f32 v9, v4, v6, -v9
	v_fma_f32 v10, v4, v7, v10
	v_add_f32_e32 v6, v9, v64
	v_add_f32_e32 v7, v10, v65
	v_cvt_pk_bf16_f32 v8, v6, v7
	global_store_dword v2, v8, s[8:9]
	s_add_u32 s8, s8, s10
	s_addc_u32 s9, s9, s11
	v_mul_f32_e32 v9, v5, v7
	v_mul_f32_e32 v10, v5, v6
	v_fma_f32 v9, v4, v6, -v9
	v_fma_f32 v10, v4, v7, v10
	v_add_f32_e32 v6, v9, v66
	v_add_f32_e32 v7, v10, v67
	v_cvt_pk_bf16_f32 v8, v6, v7
	global_store_dword v2, v8, s[8:9]
	s_add_u32 s8, s8, s10
	s_addc_u32 s9, s9, s11
	v_mul_f32_e32 v9, v5, v7
	v_mul_f32_e32 v10, v5, v6
	v_fma_f32 v9, v4, v6, -v9
	v_fma_f32 v10, v4, v7, v10
	v_add_f32_e32 v6, v9, v68
	v_add_f32_e32 v7, v10, v69
	v_cvt_pk_bf16_f32 v8, v6, v7
	global_store_dword v2, v8, s[8:9]
	s_add_u32 s8, s8, s10
	s_addc_u32 s9, s9, s11
	v_mul_f32_e32 v9, v5, v7
	v_mul_f32_e32 v10, v5, v6
	v_fma_f32 v9, v4, v6, -v9
	v_fma_f32 v10, v4, v7, v10
	v_add_f32_e32 v6, v9, v70
	v_add_f32_e32 v7, v10, v71
	v_cvt_pk_bf16_f32 v8, v6, v7
	global_store_dword v2, v8, s[8:9]
	s_add_u32 s8, s8, s10
	s_addc_u32 s9, s9, s11
	v_mul_f32_e32 v9, v5, v7
	v_mul_f32_e32 v10, v5, v6
	v_fma_f32 v9, v4, v6, -v9
	v_fma_f32 v10, v4, v7, v10
	v_add_f32_e32 v6, v9, v72
	v_add_f32_e32 v7, v10, v73
	v_cvt_pk_bf16_f32 v8, v6, v7
	global_store_dword v2, v8, s[8:9]
	s_add_u32 s8, s8, s10
	s_addc_u32 s9, s9, s11
	v_mul_f32_e32 v9, v5, v7
	v_mul_f32_e32 v10, v5, v6
	v_fma_f32 v9, v4, v6, -v9
	v_fma_f32 v10, v4, v7, v10
	v_add_f32_e32 v6, v9, v74
	v_add_f32_e32 v7, v10, v75
	v_cvt_pk_bf16_f32 v8, v6, v7
	global_store_dword v2, v8, s[8:9]
	s_add_u32 s8, s8, s10
	s_addc_u32 s9, s9, s11
	v_mul_f32_e32 v9, v5, v7
	v_mul_f32_e32 v10, v5, v6
	v_fma_f32 v9, v4, v6, -v9
	v_fma_f32 v10, v4, v7, v10
	v_add_f32_e32 v6, v9, v76
	v_add_f32_e32 v7, v10, v77
	v_cvt_pk_bf16_f32 v8, v6, v7
	global_store_dword v2, v8, s[8:9]
	s_add_u32 s8, s8, s10
	s_addc_u32 s9, s9, s11
	v_mul_f32_e32 v9, v5, v7
	v_mul_f32_e32 v10, v5, v6
	v_fma_f32 v9, v4, v6, -v9
	v_fma_f32 v10, v4, v7, v10
	v_add_f32_e32 v6, v9, v78
	v_add_f32_e32 v7, v10, v79
	v_cvt_pk_bf16_f32 v8, v6, v7
	global_store_dword v2, v8, s[8:9]
	s_add_u32 s8, s8, s10
	s_addc_u32 s9, s9, s11
	v_mul_f32_e32 v9, v5, v7
	v_mul_f32_e32 v10, v5, v6
	v_fma_f32 v9, v4, v6, -v9
	v_fma_f32 v10, v4, v7, v10
	v_add_f32_e32 v6, v9, v80
	v_add_f32_e32 v7, v10, v81
	v_cvt_pk_bf16_f32 v8, v6, v7
	global_store_dword v2, v8, s[8:9]
	s_add_u32 s8, s8, s10
	s_addc_u32 s9, s9, s11
	v_mul_f32_e32 v9, v5, v7
	v_mul_f32_e32 v10, v5, v6
	v_fma_f32 v9, v4, v6, -v9
	v_fma_f32 v10, v4, v7, v10
	v_add_f32_e32 v6, v9, v82
	v_add_f32_e32 v7, v10, v83
	v_cvt_pk_bf16_f32 v8, v6, v7
	global_store_dword v2, v8, s[8:9]
	s_add_u32 s8, s8, s10
	s_addc_u32 s9, s9, s11
	v_mul_f32_e32 v9, v5, v7
	v_mul_f32_e32 v10, v5, v6
	v_fma_f32 v9, v4, v6, -v9
	v_fma_f32 v10, v4, v7, v10
	v_add_f32_e32 v6, v9, v84
	v_add_f32_e32 v7, v10, v85
	v_cvt_pk_bf16_f32 v8, v6, v7
	global_store_dword v2, v8, s[8:9]
	s_add_u32 s8, s8, s10
	s_addc_u32 s9, s9, s11
	v_mul_f32_e32 v9, v5, v7
	v_mul_f32_e32 v10, v5, v6
	v_fma_f32 v9, v4, v6, -v9
	v_fma_f32 v10, v4, v7, v10
	v_add_f32_e32 v6, v9, v86
	v_add_f32_e32 v7, v10, v87
	v_cvt_pk_bf16_f32 v8, v6, v7
	global_store_dword v2, v8, s[8:9]
	s_add_u32 s8, s8, s10
	s_addc_u32 s9, s9, s11
	v_mul_f32_e32 v9, v5, v7
	v_mul_f32_e32 v10, v5, v6
	v_fma_f32 v9, v4, v6, -v9
	v_fma_f32 v10, v4, v7, v10
	v_add_f32_e32 v6, v9, v88
	v_add_f32_e32 v7, v10, v89
	v_cvt_pk_bf16_f32 v8, v6, v7
	global_store_dword v2, v8, s[8:9]
	s_add_u32 s8, s8, s10
	s_addc_u32 s9, s9, s11
	v_mul_f32_e32 v9, v5, v7
	v_mul_f32_e32 v10, v5, v6
	v_fma_f32 v9, v4, v6, -v9
	v_fma_f32 v10, v4, v7, v10
	v_add_f32_e32 v6, v9, v90
	v_add_f32_e32 v7, v10, v91
	v_cvt_pk_bf16_f32 v8, v6, v7
	global_store_dword v2, v8, s[8:9]
	s_add_u32 s8, s8, s10
	s_addc_u32 s9, s9, s11
	v_mul_f32_e32 v9, v5, v7
	v_mul_f32_e32 v10, v5, v6
	v_fma_f32 v9, v4, v6, -v9
	v_fma_f32 v10, v4, v7, v10
	v_add_f32_e32 v6, v9, v92
	v_add_f32_e32 v7, v10, v93
	v_cvt_pk_bf16_f32 v8, v6, v7
	global_store_dword v2, v8, s[8:9]
	s_add_u32 s8, s8, s10
	s_addc_u32 s9, s9, s11
	v_mul_f32_e32 v9, v5, v7
	v_mul_f32_e32 v10, v5, v6
	v_fma_f32 v9, v4, v6, -v9
	v_fma_f32 v10, v4, v7, v10
	v_add_f32_e32 v6, v9, v94
	v_add_f32_e32 v7, v10, v95
	s_lshl_b32 s17, s16, 1
	s_add_i32 s17, s17, s25
	s_lshl_b32 s17, s17, 5
	s_add_i32 s17, s17, s20
	s_lshl_b32 s17, s17, 8
	s_add_u32 s62, s52, s17
	s_addc_u32 s63, s53, 0
	s_add_u32 s62, s62, 0x4000000
	s_addc_u32 s63, s63, 0
	global_store_dword v2, v6, s[62:63]
	s_add_u32 s62, s62, 0x40000
	s_addc_u32 s63, s63, 0
	global_store_dword v2, v7, s[62:63]
	s_add_i32 s16, s21, 12
	s_lshl_b32 s19, s16, 4
	s_mul_i32 s17, s20, 0x300
	s_add_i32 s17, s17, s19
	s_mul_i32 s18, s25, 15
	s_add_i32 s17, s17, s18
	s_lshl_b32 s17, s17, 10
	s_lshl_b32 s18, s25, 9
	s_add_u32 s0, s54, 0x4200000
	s_addc_u32 s1, s55, 0
	s_add_u32 s0, s0, s17
	s_addc_u32 s1, s1, 0
	s_add_u32 s0, s0, s18
	s_addc_u32 s1, s1, 0
	s_lshl_b32 s18, s25, 8
	s_add_u32 s8, s54, 0xa200000
	s_addc_u32 s9, s55, 0
	s_add_u32 s8, s8, s17
	s_addc_u32 s9, s9, 0
	s_add_u32 s8, s8, s18
	s_addc_u32 s9, s9, 0
	s_add_u32 s8, s8, 0x200
	s_addc_u32 s9, s9, 0
	global_load_dwordx2 v[32:33], v1, s[0:1]
	s_add_u32 s0, s0, s10
	s_addc_u32 s1, s1, s11
	global_load_dwordx2 v[34:35], v1, s[0:1]
	s_add_u32 s0, s0, s10
	s_addc_u32 s1, s1, s11
	global_load_dwordx2 v[36:37], v1, s[0:1]
	s_add_u32 s0, s0, s10
	s_addc_u32 s1, s1, s11
	global_load_dwordx2 v[38:39], v1, s[0:1]
	s_add_u32 s0, s0, s10
	s_addc_u32 s1, s1, s11
	global_load_dwordx2 v[40:41], v1, s[0:1]
	s_add_u32 s0, s0, s10
	s_addc_u32 s1, s1, s11
	global_load_dwordx2 v[42:43], v1, s[0:1]
	s_add_u32 s0, s0, s10
	s_addc_u32 s1, s1, s11
	global_load_dwordx2 v[44:45], v1, s[0:1]
	s_add_u32 s0, s0, s10
	s_addc_u32 s1, s1, s11
	global_load_dwordx2 v[46:47], v1, s[0:1]
	s_add_u32 s0, s0, s10
	s_addc_u32 s1, s1, s11
	global_load_dwordx2 v[48:49], v1, s[0:1]
	s_add_u32 s0, s0, s10
	s_addc_u32 s1, s1, s11
	global_load_dwordx2 v[50:51], v1, s[0:1]
	s_add_u32 s0, s0, s10
	s_addc_u32 s1, s1, s11
	global_load_dwordx2 v[52:53], v1, s[0:1]
	s_add_u32 s0, s0, s10
	s_addc_u32 s1, s1, s11
	global_load_dwordx2 v[54:55], v1, s[0:1]
	s_add_u32 s0, s0, s10
	s_addc_u32 s1, s1, s11
	global_load_dwordx2 v[56:57], v1, s[0:1]
	s_add_u32 s0, s0, s10
	s_addc_u32 s1, s1, s11
	global_load_dwordx2 v[58:59], v1, s[0:1]
	s_add_u32 s0, s0, s10
	s_addc_u32 s1, s1, s11
	global_load_dwordx2 v[60:61], v1, s[0:1]
	s_add_u32 s0, s0, s10
	s_addc_u32 s1, s1, s11
	global_load_dwordx2 v[62:63], v1, s[0:1]
	s_add_u32 s0, s0, s10
	s_addc_u32 s1, s1, s11
	s_add_i32 s16, s21, 8
	s_lshl_b32 s19, s16, 4
	s_mul_i32 s17, s20, 0x300
	s_add_i32 s17, s17, s19
	s_mul_i32 s18, s25, 15
	s_add_i32 s17, s17, s18
	s_lshl_b32 s17, s17, 10
	s_lshl_b32 s18, s25, 8
	s_add_u32 s8, s54, 0xa200000
	s_addc_u32 s9, s55, 0
	s_add_u32 s8, s8, s17
	s_addc_u32 s9, s9, 0
	s_add_u32 s8, s8, s18
	s_addc_u32 s9, s9, 0
	s_add_u32 s8, s8, 0x200
	s_addc_u32 s9, s9, 0
	v_mov_b32_e32 v6, 0
	v_mov_b32_e32 v7, 0
	s_waitcnt vmcnt(34)
	v_cvt_pk_bf16_f32 v8, v6, v7
	global_store_dword v2, v8, s[8:9]
	s_add_u32 s8, s8, s10
	s_addc_u32 s9, s9, s11
	v_mul_f32_e32 v9, v5, v7
	v_mul_f32_e32 v10, v5, v6
	v_fma_f32 v9, v4, v6, -v9
	v_fma_f32 v10, v4, v7, v10
	v_add_f32_e32 v6, v9, v96
	v_add_f32_e32 v7, v10, v97
	v_cvt_pk_bf16_f32 v8, v6, v7
	global_store_dword v2, v8, s[8:9]
	s_add_u32 s8, s8, s10
	s_addc_u32 s9, s9, s11
	v_mul_f32_e32 v9, v5, v7
	v_mul_f32_e32 v10, v5, v6
	v_fma_f32 v9, v4, v6, -v9
	v_fma_f32 v10, v4, v7, v10
	v_add_f32_e32 v6, v9, v98
	v_add_f32_e32 v7, v10, v99
	v_cvt_pk_bf16_f32 v8, v6, v7
	global_store_dword v2, v8, s[8:9]
	s_add_u32 s8, s8, s10
	s_addc_u32 s9, s9, s11
	v_mul_f32_e32 v9, v5, v7
	v_mul_f32_e32 v10, v5, v6
	v_fma_f32 v9, v4, v6, -v9
	v_fma_f32 v10, v4, v7, v10
	v_add_f32_e32 v6, v9, v100
	v_add_f32_e32 v7, v10, v101
	v_cvt_pk_bf16_f32 v8, v6, v7
	global_store_dword v2, v8, s[8:9]
	s_add_u32 s8, s8, s10
	s_addc_u32 s9, s9, s11
	v_mul_f32_e32 v9, v5, v7
	v_mul_f32_e32 v10, v5, v6
	v_fma_f32 v9, v4, v6, -v9
	v_fma_f32 v10, v4, v7, v10
	v_add_f32_e32 v6, v9, v102
	v_add_f32_e32 v7, v10, v103
	v_cvt_pk_bf16_f32 v8, v6, v7
	global_store_dword v2, v8, s[8:9]
	s_add_u32 s8, s8, s10
	s_addc_u32 s9, s9, s11
	v_mul_f32_e32 v9, v5, v7
	v_mul_f32_e32 v10, v5, v6
	v_fma_f32 v9, v4, v6, -v9
	v_fma_f32 v10, v4, v7, v10
	v_add_f32_e32 v6, v9, v104
	v_add_f32_e32 v7, v10, v105
	v_cvt_pk_bf16_f32 v8, v6, v7
	global_store_dword v2, v8, s[8:9]
	s_add_u32 s8, s8, s10
	s_addc_u32 s9, s9, s11
	v_mul_f32_e32 v9, v5, v7
	v_mul_f32_e32 v10, v5, v6
	v_fma_f32 v9, v4, v6, -v9
	v_fma_f32 v10, v4, v7, v10
	v_add_f32_e32 v6, v9, v106
	v_add_f32_e32 v7, v10, v107
	v_cvt_pk_bf16_f32 v8, v6, v7
	global_store_dword v2, v8, s[8:9]
	s_add_u32 s8, s8, s10
	s_addc_u32 s9, s9, s11
	v_mul_f32_e32 v9, v5, v7
	v_mul_f32_e32 v10, v5, v6
	v_fma_f32 v9, v4, v6, -v9
	v_fma_f32 v10, v4, v7, v10
	v_add_f32_e32 v6, v9, v108
	v_add_f32_e32 v7, v10, v109
	v_cvt_pk_bf16_f32 v8, v6, v7
	global_store_dword v2, v8, s[8:9]
	s_add_u32 s8, s8, s10
	s_addc_u32 s9, s9, s11
	v_mul_f32_e32 v9, v5, v7
	v_mul_f32_e32 v10, v5, v6
	v_fma_f32 v9, v4, v6, -v9
	v_fma_f32 v10, v4, v7, v10
	v_add_f32_e32 v6, v9, v110
	v_add_f32_e32 v7, v10, v111
	v_cvt_pk_bf16_f32 v8, v6, v7
	global_store_dword v2, v8, s[8:9]
	s_add_u32 s8, s8, s10
	s_addc_u32 s9, s9, s11
	v_mul_f32_e32 v9, v5, v7
	v_mul_f32_e32 v10, v5, v6
	v_fma_f32 v9, v4, v6, -v9
	v_fma_f32 v10, v4, v7, v10
	v_add_f32_e32 v6, v9, v112
	v_add_f32_e32 v7, v10, v113
	v_cvt_pk_bf16_f32 v8, v6, v7
	global_store_dword v2, v8, s[8:9]
	s_add_u32 s8, s8, s10
	s_addc_u32 s9, s9, s11
	v_mul_f32_e32 v9, v5, v7
	v_mul_f32_e32 v10, v5, v6
	v_fma_f32 v9, v4, v6, -v9
	v_fma_f32 v10, v4, v7, v10
	v_add_f32_e32 v6, v9, v114
	v_add_f32_e32 v7, v10, v115
	v_cvt_pk_bf16_f32 v8, v6, v7
	global_store_dword v2, v8, s[8:9]
	s_add_u32 s8, s8, s10
	s_addc_u32 s9, s9, s11
	v_mul_f32_e32 v9, v5, v7
	v_mul_f32_e32 v10, v5, v6
	v_fma_f32 v9, v4, v6, -v9
	v_fma_f32 v10, v4, v7, v10
	v_add_f32_e32 v6, v9, v116
	v_add_f32_e32 v7, v10, v117
	v_cvt_pk_bf16_f32 v8, v6, v7
	global_store_dword v2, v8, s[8:9]
	s_add_u32 s8, s8, s10
	s_addc_u32 s9, s9, s11
	v_mul_f32_e32 v9, v5, v7
	v_mul_f32_e32 v10, v5, v6
	v_fma_f32 v9, v4, v6, -v9
	v_fma_f32 v10, v4, v7, v10
	v_add_f32_e32 v6, v9, v118
	v_add_f32_e32 v7, v10, v119
	v_cvt_pk_bf16_f32 v8, v6, v7
	global_store_dword v2, v8, s[8:9]
	s_add_u32 s8, s8, s10
	s_addc_u32 s9, s9, s11
	v_mul_f32_e32 v9, v5, v7
	v_mul_f32_e32 v10, v5, v6
	v_fma_f32 v9, v4, v6, -v9
	v_fma_f32 v10, v4, v7, v10
	v_add_f32_e32 v6, v9, v120
	v_add_f32_e32 v7, v10, v121
	v_cvt_pk_bf16_f32 v8, v6, v7
	global_store_dword v2, v8, s[8:9]
	s_add_u32 s8, s8, s10
	s_addc_u32 s9, s9, s11
	v_mul_f32_e32 v9, v5, v7
	v_mul_f32_e32 v10, v5, v6
	v_fma_f32 v9, v4, v6, -v9
	v_fma_f32 v10, v4, v7, v10
	v_add_f32_e32 v6, v9, v122
	v_add_f32_e32 v7, v10, v123
	v_cvt_pk_bf16_f32 v8, v6, v7
	global_store_dword v2, v8, s[8:9]
	s_add_u32 s8, s8, s10
	s_addc_u32 s9, s9, s11
	v_mul_f32_e32 v9, v5, v7
	v_mul_f32_e32 v10, v5, v6
	v_fma_f32 v9, v4, v6, -v9
	v_fma_f32 v10, v4, v7, v10
	v_add_f32_e32 v6, v9, v124
	v_add_f32_e32 v7, v10, v125
	v_cvt_pk_bf16_f32 v8, v6, v7
	global_store_dword v2, v8, s[8:9]
	s_add_u32 s8, s8, s10
	s_addc_u32 s9, s9, s11
	v_mul_f32_e32 v9, v5, v7
	v_mul_f32_e32 v10, v5, v6
	v_fma_f32 v9, v4, v6, -v9
	v_fma_f32 v10, v4, v7, v10
	v_add_f32_e32 v6, v9, v126
	v_add_f32_e32 v7, v10, v127
	s_lshl_b32 s17, s16, 1
	s_add_i32 s17, s17, s25
	s_lshl_b32 s17, s17, 5
	s_add_i32 s17, s17, s20
	s_lshl_b32 s17, s17, 8
	s_add_u32 s62, s52, s17
	s_addc_u32 s63, s53, 0
	s_add_u32 s62, s62, 0x4000000
	s_addc_u32 s63, s63, 0
	global_store_dword v2, v6, s[62:63]
	s_add_u32 s62, s62, 0x40000
	s_addc_u32 s63, s63, 0
	global_store_dword v2, v7, s[62:63]
	s_add_i32 s16, s21, 12
	s_lshl_b32 s19, s16, 4
	s_mul_i32 s17, s20, 0x300
	s_add_i32 s17, s17, s19
	s_mul_i32 s18, s25, 15
	s_add_i32 s17, s17, s18
	s_lshl_b32 s17, s17, 10
	s_lshl_b32 s18, s25, 8
	s_add_u32 s8, s54, 0xa200000
	s_addc_u32 s9, s55, 0
	s_add_u32 s8, s8, s17
	s_addc_u32 s9, s9, 0
	s_add_u32 s8, s8, s18
	s_addc_u32 s9, s9, 0
	s_add_u32 s8, s8, 0x200
	s_addc_u32 s9, s9, 0
	v_mov_b32_e32 v6, 0
	v_mov_b32_e32 v7, 0
	s_waitcnt vmcnt(18)
	v_cvt_pk_bf16_f32 v8, v6, v7
	global_store_dword v2, v8, s[8:9]
	s_add_u32 s8, s8, s10
	s_addc_u32 s9, s9, s11
	v_mul_f32_e32 v9, v5, v7
	v_mul_f32_e32 v10, v5, v6
	v_fma_f32 v9, v4, v6, -v9
	v_fma_f32 v10, v4, v7, v10
	v_add_f32_e32 v6, v9, v32
	v_add_f32_e32 v7, v10, v33
	v_cvt_pk_bf16_f32 v8, v6, v7
	global_store_dword v2, v8, s[8:9]
	s_add_u32 s8, s8, s10
	s_addc_u32 s9, s9, s11
	v_mul_f32_e32 v9, v5, v7
	v_mul_f32_e32 v10, v5, v6
	v_fma_f32 v9, v4, v6, -v9
	v_fma_f32 v10, v4, v7, v10
	v_add_f32_e32 v6, v9, v34
	v_add_f32_e32 v7, v10, v35
	v_cvt_pk_bf16_f32 v8, v6, v7
	global_store_dword v2, v8, s[8:9]
	s_add_u32 s8, s8, s10
	s_addc_u32 s9, s9, s11
	v_mul_f32_e32 v9, v5, v7
	v_mul_f32_e32 v10, v5, v6
	v_fma_f32 v9, v4, v6, -v9
	v_fma_f32 v10, v4, v7, v10
	v_add_f32_e32 v6, v9, v36
	v_add_f32_e32 v7, v10, v37
	v_cvt_pk_bf16_f32 v8, v6, v7
	global_store_dword v2, v8, s[8:9]
	s_add_u32 s8, s8, s10
	s_addc_u32 s9, s9, s11
	v_mul_f32_e32 v9, v5, v7
	v_mul_f32_e32 v10, v5, v6
	v_fma_f32 v9, v4, v6, -v9
	v_fma_f32 v10, v4, v7, v10
	v_add_f32_e32 v6, v9, v38
	v_add_f32_e32 v7, v10, v39
	v_cvt_pk_bf16_f32 v8, v6, v7
	global_store_dword v2, v8, s[8:9]
	s_add_u32 s8, s8, s10
	s_addc_u32 s9, s9, s11
	v_mul_f32_e32 v9, v5, v7
	v_mul_f32_e32 v10, v5, v6
	v_fma_f32 v9, v4, v6, -v9
	v_fma_f32 v10, v4, v7, v10
	v_add_f32_e32 v6, v9, v40
	v_add_f32_e32 v7, v10, v41
	v_cvt_pk_bf16_f32 v8, v6, v7
	global_store_dword v2, v8, s[8:9]
	s_add_u32 s8, s8, s10
	s_addc_u32 s9, s9, s11
	v_mul_f32_e32 v9, v5, v7
	v_mul_f32_e32 v10, v5, v6
	v_fma_f32 v9, v4, v6, -v9
	v_fma_f32 v10, v4, v7, v10
	v_add_f32_e32 v6, v9, v42
	v_add_f32_e32 v7, v10, v43
	v_cvt_pk_bf16_f32 v8, v6, v7
	global_store_dword v2, v8, s[8:9]
	s_add_u32 s8, s8, s10
	s_addc_u32 s9, s9, s11
	v_mul_f32_e32 v9, v5, v7
	v_mul_f32_e32 v10, v5, v6
	v_fma_f32 v9, v4, v6, -v9
	v_fma_f32 v10, v4, v7, v10
	v_add_f32_e32 v6, v9, v44
	v_add_f32_e32 v7, v10, v45
	v_cvt_pk_bf16_f32 v8, v6, v7
	global_store_dword v2, v8, s[8:9]
	s_add_u32 s8, s8, s10
	s_addc_u32 s9, s9, s11
	v_mul_f32_e32 v9, v5, v7
	v_mul_f32_e32 v10, v5, v6
	v_fma_f32 v9, v4, v6, -v9
	v_fma_f32 v10, v4, v7, v10
	v_add_f32_e32 v6, v9, v46
	v_add_f32_e32 v7, v10, v47
	v_cvt_pk_bf16_f32 v8, v6, v7
	global_store_dword v2, v8, s[8:9]
	s_add_u32 s8, s8, s10
	s_addc_u32 s9, s9, s11
	v_mul_f32_e32 v9, v5, v7
	v_mul_f32_e32 v10, v5, v6
	v_fma_f32 v9, v4, v6, -v9
	v_fma_f32 v10, v4, v7, v10
	v_add_f32_e32 v6, v9, v48
	v_add_f32_e32 v7, v10, v49
	v_cvt_pk_bf16_f32 v8, v6, v7
	global_store_dword v2, v8, s[8:9]
	s_add_u32 s8, s8, s10
	s_addc_u32 s9, s9, s11
	v_mul_f32_e32 v9, v5, v7
	v_mul_f32_e32 v10, v5, v6
	v_fma_f32 v9, v4, v6, -v9
	v_fma_f32 v10, v4, v7, v10
	v_add_f32_e32 v6, v9, v50
	v_add_f32_e32 v7, v10, v51
	v_cvt_pk_bf16_f32 v8, v6, v7
	global_store_dword v2, v8, s[8:9]
	s_add_u32 s8, s8, s10
	s_addc_u32 s9, s9, s11
	v_mul_f32_e32 v9, v5, v7
	v_mul_f32_e32 v10, v5, v6
	v_fma_f32 v9, v4, v6, -v9
	v_fma_f32 v10, v4, v7, v10
	v_add_f32_e32 v6, v9, v52
	v_add_f32_e32 v7, v10, v53
	v_cvt_pk_bf16_f32 v8, v6, v7
	global_store_dword v2, v8, s[8:9]
	s_add_u32 s8, s8, s10
	s_addc_u32 s9, s9, s11
	v_mul_f32_e32 v9, v5, v7
	v_mul_f32_e32 v10, v5, v6
	v_fma_f32 v9, v4, v6, -v9
	v_fma_f32 v10, v4, v7, v10
	v_add_f32_e32 v6, v9, v54
	v_add_f32_e32 v7, v10, v55
	v_cvt_pk_bf16_f32 v8, v6, v7
	global_store_dword v2, v8, s[8:9]
	s_add_u32 s8, s8, s10
	s_addc_u32 s9, s9, s11
	v_mul_f32_e32 v9, v5, v7
	v_mul_f32_e32 v10, v5, v6
	v_fma_f32 v9, v4, v6, -v9
	v_fma_f32 v10, v4, v7, v10
	v_add_f32_e32 v6, v9, v56
	v_add_f32_e32 v7, v10, v57
	v_cvt_pk_bf16_f32 v8, v6, v7
	global_store_dword v2, v8, s[8:9]
	s_add_u32 s8, s8, s10
	s_addc_u32 s9, s9, s11
	v_mul_f32_e32 v9, v5, v7
	v_mul_f32_e32 v10, v5, v6
	v_fma_f32 v9, v4, v6, -v9
	v_fma_f32 v10, v4, v7, v10
	v_add_f32_e32 v6, v9, v58
	v_add_f32_e32 v7, v10, v59
	v_cvt_pk_bf16_f32 v8, v6, v7
	global_store_dword v2, v8, s[8:9]
	s_add_u32 s8, s8, s10
	s_addc_u32 s9, s9, s11
	v_mul_f32_e32 v9, v5, v7
	v_mul_f32_e32 v10, v5, v6
	v_fma_f32 v9, v4, v6, -v9
	v_fma_f32 v10, v4, v7, v10
	v_add_f32_e32 v6, v9, v60
	v_add_f32_e32 v7, v10, v61
	v_cvt_pk_bf16_f32 v8, v6, v7
	global_store_dword v2, v8, s[8:9]
	s_add_u32 s8, s8, s10
	s_addc_u32 s9, s9, s11
	v_mul_f32_e32 v9, v5, v7
	v_mul_f32_e32 v10, v5, v6
	v_fma_f32 v9, v4, v6, -v9
	v_fma_f32 v10, v4, v7, v10
	v_add_f32_e32 v6, v9, v62
	v_add_f32_e32 v7, v10, v63
	s_lshl_b32 s17, s16, 1
	s_add_i32 s17, s17, s25
	s_lshl_b32 s17, s17, 5
	s_add_i32 s17, s17, s20
	s_lshl_b32 s17, s17, 8
	s_add_u32 s62, s52, s17
	s_addc_u32 s63, s53, 0
	s_add_u32 s62, s62, 0x4000000
	s_addc_u32 s63, s63, 0
	global_store_dword v2, v6, s[62:63]
	s_add_u32 s62, s62, 0x40000
	s_addc_u32 s63, s63, 0
	global_store_dword v2, v7, s[62:63]
.Lscan_end:
	s_waitcnt vmcnt(0)
	s_barrier
.LBB0_910:
	s_and_b64 vcc, exec, s[6:7]
	v_mbcnt_lo_u32_b32 v9, -1, 0
	v_mbcnt_hi_u32_b32 v9, -1, v9
	s_cbranch_vccnz .LBB0_924
	v_lshl_add_u32 v0, v9, 4, s84
	v_add_u32_e32 v1, 0x2000, v0
	v_ashrrev_i32_e32 v2, 31, v1
	v_lshrrev_b32_e32 v2, 22, v2
	v_add_u32_e32 v2, v1, v2
	v_ashrrev_i32_e32 v8, 10, v2
	v_mul_i32_i24_e32 v2, 0x400, v8
	v_sub_u32_e32 v1, v1, v2
	v_lshrrev_b32_e32 v2, 4, v1
	v_bitop3_b32 v1, v2, v1, 32 bitop3:0x6c
	v_ashrrev_i32_e32 v2, 31, v1
	v_lshrrev_b32_e32 v2, 26, v2
	v_add_u32_e32 v2, v1, v2
	v_ashrrev_i32_e32 v10, 6, v2
	v_lshlrev_b32_e32 v3, 3, v8
	v_and_b32_e32 v2, 0xffc0, v2
	v_and_b32_e32 v3, -16, v3
	v_sub_u32_e32 v1, v1, v2
	v_add_u32_e32 v3, v10, v3
	v_lshrrev_b16_e32 v2, 7, v1
	v_and_b32_e32 v4, 3, v10
	s_mov_b32 s8, 0x3fffe0
	v_lshrrev_b32_e32 v5, 2, v3
	v_lshlrev_b32_e32 v6, 1, v3
	v_and_b32_e32 v2, 1, v2
	v_and_or_b32 v4, v3, s8, v4
	v_and_b32_e32 v5, 4, v5
	v_and_b32_e32 v6, 24, v6
	v_add_u16_e32 v1, v1, v2
	v_mov_b32_e32 v2, 1
	v_or3_b32 v4, v4, v5, v6
	v_lshlrev_b32_e32 v5, 5, v8
	v_ashrrev_i16_sdwa v1, v2, sext(v1) dst_sel:DWORD dst_unused:UNUSED_PAD src0_sel:DWORD src1_sel:BYTE_0
	v_and_b32_e32 v5, 32, v5
	v_bfe_i32 v11, v1, 0, 16
	v_add_lshl_u32 v1, v5, v11, 1
	v_lshl_add_u32 v128, v4, 10, v1
	v_lshl_add_u32 v130, v3, 10, v1
	v_ashrrev_i32_e32 v1, 31, v0
	v_lshrrev_b32_e32 v1, 22, v1
	v_add_u32_e32 v1, v0, v1
	s_waitcnt vmcnt(28)
	v_ashrrev_i32_e32 v12, 10, v1
	v_mul_i32_i24_e32 v1, 0x400, v12
	v_sub_u32_e32 v0, v0, v1
	v_lshrrev_b32_e32 v1, 4, v0
	v_bitop3_b32 v0, v1, v0, 32 bitop3:0x6c
	v_ashrrev_i32_e32 v1, 31, v0
	v_lshrrev_b32_e32 v1, 26, v1
	v_add_u32_e32 v1, v0, v1
	v_lshlrev_b32_e32 v3, 3, v12
	v_ashrrev_i32_e32 v13, 6, v1
	v_and_b32_e32 v3, -16, v3
	v_add_u32_e32 v3, v13, v3
	v_and_b32_e32 v4, 3, v13
	v_lshrrev_b32_e32 v5, 2, v3
	v_lshlrev_b32_e32 v6, 1, v3
	v_and_b32_e32 v1, 0xc0, v1
	s_add_u32 s0, s12, s68
	v_and_or_b32 v4, v3, s8, v4
	v_and_b32_e32 v5, 4, v5
	v_and_b32_e32 v6, 24, v6
	v_sub_u32_e32 v0, v0, v1
	s_addc_u32 s1, s13, s69
	v_or3_b32 v4, v4, v5, v6
	v_lshlrev_b32_e32 v5, 5, v12
	v_ashrrev_i16_sdwa v0, v2, sext(v0) dst_sel:DWORD dst_unused:UNUSED_PAD src0_sel:DWORD src1_sel:BYTE_0
	s_add_u32 s6, s0, 0x20000
	v_and_b32_e32 v5, 32, v5
	v_bfe_i32 v14, v0, 0, 16
	s_addc_u32 s7, s1, 0
	v_add_lshl_u32 v0, v5, v14, 1
	s_add_i32 s21, s84, 0
	v_lshl_add_u32 v132, v4, 10, v0
	s_add_i32 m0, s21, 0x10000
	v_lshl_add_u32 v134, v3, 10, v0
	global_load_lds_dwordx4 v132, s[0:1]
	s_add_i32 m0, s21, 0x12000
	s_add_i32 s70, s21, 0x2000
	global_load_lds_dwordx4 v128, s[0:1]
	s_add_i32 m0, s21, 0x14000
	s_add_i32 s71, s21, 0x4000
	global_load_lds_dwordx4 v132, s[6:7]
	s_add_i32 m0, s21, 0x16000
	s_add_i32 s72, s21, 0x6000
	global_load_lds_dwordx4 v128, s[6:7]
	s_mov_b32 m0, s21
	v_mov_b32_e32 v137, 0
	global_load_lds_dwordx4 v134, s[64:65]
	s_mov_b32 m0, s70
	v_mov_b32_e32 v133, v137
	global_load_lds_dwordx4 v130, s[64:65]
	s_mov_b32 m0, s71
	v_mov_b32_e32 v129, v137
	global_load_lds_dwordx4 v134, s[66:67]
	s_mov_b32 m0, s72
	v_mov_b32_e32 v135, v137
	global_load_lds_dwordx4 v130, s[66:67]
	v_mov_b32_e32 v131, v137
	v_lshl_add_u64 v[6:7], s[0:1], 0, v[132:133]
	s_mov_b32 s8, 0
	v_lshl_add_u64 v[4:5], s[0:1], 0, v[128:129]
	v_lshl_add_u64 v[2:3], s[64:65], 0, v[134:135]
	s_and_b64 vcc, exec, s[4:5]
	v_lshl_add_u64 v[0:1], s[64:65], 0, v[130:131]
	s_cbranch_vccnz .LBB0_913
	s_barrier
